# EpiUp epilogue: row statistics loaded once per row panel (one 16B load per lane per row + permlane reduce) instead of 8 load-wait round trips; attention: next-tile K prefetch lands in its own register
# speedup vs baseline: 1.0240x; 1.0240x over previous
; #define LAS __attribute__((address_space(3)))
; __device__ __forceinline__ void attn_unit(const AttnP& P, LAS unsigned char* lds, int b, int hd, int qq, int wave, int lane) {
;     int tid_ = threadIdx.x; asm volatile("" : "+v"(tid_));
;     const int hb = b * 8 + hd, tid = tid_;
;     float shift;
;     { const float mq = wave_max(fabsf(P.gq[lane])), mk = wave_max(fabsf(P.gk[lane])); shift = fminf(8.0f * mq * mk * 1.4426950408889634f, 64.0f); shift = shift > 30.0f ? shift : 0.f; }
;     {
;         u32x4 kr[8], vr[8];
; #pragma unroll
;         for (int j = 0; j < 8; ++j) { const int chunk = tid + 512 * j, row = chunk >> 3, piece = chunk & 7, cls = row >> 5, il = row & 31;
;             kr[j] = *(const u32x4*)(P.K + ((size_t)(hb * 16 + cls) * 128 + 32 * qq + il) * 64 + piece * 8); }
; #pragma unroll
;         for (int j = 0; j < 8; ++j) { const int chunk = tid + 512 * j, cls = chunk >> 8, within = chunk & 255;
;             vr[j] = *(const u32x4*)(P.Vt + ((size_t)(hb * 16 + cls) * 16 + 4 * qq) * 512 + within * 8); }
;         __syncthreads();
.LBB0_169:
	v_mov_b32_e32 v1, v0
	global_load_dword v32, v[192:193], off
	global_load_dword v33, v[194:195], off
	v_cmp_lt_i32_e32 vcc, v217, v216
	s_bfe_u32 s18, s97, 0x40004
	s_and_b32 s98, s97, 7
	v_cndmask_b32_e32 v2, v215, v217, vcc
	v_cmp_lt_i32_e32 vcc, v218, v216
	s_lshl_b32 s0, s18, 3
	s_or_b32 s0, s0, s98
	v_cndmask_b32_e32 v3, v215, v218, vcc
	v_cmp_lt_i32_e32 vcc, v219, v216
	v_add_u32_e32 v70, 0x200, v1
	v_add_u32_e32 v71, 0x400, v1
	v_cndmask_b32_e32 v4, v215, v219, vcc
	v_cmp_lt_i32_e32 vcc, v220, v216
	v_lshlrev_b32_e32 v223, 2, v4
	s_lshl_b32 s99, s0, 4
	v_cndmask_b32_e32 v5, v215, v220, vcc
	v_ashrrev_i32_e32 v4, 8, v70
	s_bfe_u32 s12, s97, 0x10003
	v_lshlrev_b32_e32 v199, 2, v5
	v_lshlrev_b32_e32 v67, 4, v1
	v_ashrrev_i32_e32 v5, 8, v71
	v_add_u32_e32 v4, s99, v4
	s_xor_b32 s1, s12, 3
	v_and_b32_e32 v190, 0x70, v67
	v_add_u32_e32 v6, s99, v5
	v_ashrrev_i32_e32 v5, 31, v4
	v_lshlrev_b32_e32 v224, 2, v3
	s_lshl_b32 s4, s1, 12
	v_and_b32_e32 v3, 0xf80, v67
	v_lshl_add_u64 v[28:29], s[50:51], 0, v[190:191]
	v_lshlrev_b64 v[36:37], 14, v[4:5]
	v_mov_b32_e32 v27, v191
	v_or_b32_e32 v26, s4, v3
	v_lshl_add_u64 v[4:5], v[28:29], 0, v[36:37]
	v_lshlrev_b32_e32 v225, 2, v2
	v_ashrrev_i32_e32 v2, 8, v1
	v_add_u32_e32 v72, 0x600, v1
	v_add_u32_e32 v73, 0x800, v1
	v_add_u32_e32 v74, 0xa00, v1
	v_add_u32_e32 v75, 0xc00, v1
	v_lshl_add_u64 v[16:17], v[4:5], 0, v[26:27]
	v_ashrrev_i32_e32 v7, 8, v72
	v_ashrrev_i32_e32 v9, 8, v73
	v_ashrrev_i32_e32 v11, 8, v74
	v_ashrrev_i32_e32 v13, 8, v75
	v_add_u32_e32 v2, s99, v2
	v_add_u32_e32 v8, s99, v7
	v_add_u32_e32 v10, s99, v9
	v_add_u32_e32 v12, s99, v11
	v_add_u32_e32 v14, s99, v13
	v_ashrrev_i32_e32 v3, 31, v2
	v_ashrrev_i32_e32 v7, 31, v6
	v_ashrrev_i32_e32 v9, 31, v8
	v_ashrrev_i32_e32 v11, 31, v10
	v_ashrrev_i32_e32 v13, 31, v12
	v_ashrrev_i32_e32 v15, 31, v14
	v_lshlrev_b64 v[34:35], 14, v[2:3]
	v_lshlrev_b64 v[42:43], 14, v[6:7]
	v_lshlrev_b64 v[44:45], 14, v[8:9]
	v_lshlrev_b64 v[50:51], 14, v[10:11]
	v_lshlrev_b64 v[52:53], 14, v[12:13]
	v_lshlrev_b64 v[58:59], 14, v[14:15]
	v_lshl_add_u64 v[2:3], v[28:29], 0, v[34:35]
	v_lshl_add_u64 v[6:7], v[28:29], 0, v[42:43]
	v_lshl_add_u64 v[8:9], v[28:29], 0, v[44:45]
	v_lshl_add_u64 v[10:11], v[28:29], 0, v[50:51]
	v_lshl_add_u64 v[12:13], v[28:29], 0, v[52:53]
	v_lshl_add_u64 v[14:15], v[28:29], 0, v[58:59]
	v_lshl_add_u64 v[2:3], v[2:3], 0, v[26:27]
	v_lshl_add_u64 v[18:19], v[6:7], 0, v[26:27]
	v_lshl_add_u64 v[20:21], v[8:9], 0, v[26:27]
	v_lshl_add_u64 v[22:23], v[10:11], 0, v[26:27]
	v_lshl_add_u64 v[24:25], v[12:13], 0, v[26:27]
	v_lshl_add_u64 v[30:31], v[14:15], 0, v[26:27]
	v_add_u32_e32 v76, 0xe00, v1
	v_ashrrev_i32_e32 v38, 8, v76
	s_add_u32 s4, s52, s4
	s_addc_u32 s5, s53, 0
	s_waitcnt vmcnt(1)
	v_and_b32_e32 v4, 0x7fffffff, v32
	ds_bpermute_b32 v39, v225, v4
	global_load_dwordx4 v[2:5], v[2:3], off
	s_nop 0
	global_load_dwordx4 v[6:9], v[16:17], off
	global_load_dwordx4 v[10:13], v[18:19], off
	s_nop 0
	global_load_dwordx4 v[14:17], v[20:21], off
	v_max_f32_e64 v18, |v32|, |v32|
	s_waitcnt vmcnt(4)
	v_and_b32_e32 v40, 0x7fffffff, v33
	ds_bpermute_b32 v40, v225, v40
	s_waitcnt lgkmcnt(1)
	v_max_f32_e32 v19, v39, v39
	v_max_f32_e32 v32, v18, v19
	ds_bpermute_b32 v39, v224, v32
	v_max_f32_e64 v33, |v33|, |v33|
	s_waitcnt lgkmcnt(1)
	v_max_f32_e32 v40, v40, v40
	v_max_f32_e32 v66, v33, v40
	global_load_dwordx4 v[18:21], v[22:23], off
	s_nop 0
	global_load_dwordx4 v[22:25], v[24:25], off
	s_waitcnt lgkmcnt(0)
	v_max_f32_e32 v39, v39, v39
	v_max_f32_e32 v32, v32, v39
	ds_bpermute_b32 v39, v223, v32
	ds_bpermute_b32 v68, v224, v66
	v_cmp_lt_i32_e32 vcc, v221, v216
	v_lshrrev_b32_e32 v1, 3, v1
	v_mov_b32_e32 v228, v201
	s_waitcnt lgkmcnt(1)
	v_max_f32_e32 v33, v39, v39
	v_max_f32_e32 v69, v32, v33
	v_add_u32_e32 v32, s99, v38
	v_ashrrev_i32_e32 v33, 31, v32
	v_lshlrev_b64 v[60:61], 14, v[32:33]
	v_and_b32_e32 v38, 0xff0, v67
	v_mov_b32_e32 v39, v191
	v_lshl_add_u64 v[28:29], v[28:29], 0, v[60:61]
	v_lshl_add_u64 v[62:63], s[4:5], 0, v[38:39]
	v_lshl_add_u64 v[32:33], v[28:29], 0, v[26:27]
	v_lshl_add_u64 v[34:35], v[62:63], 0, v[34:35]
	v_lshl_add_u64 v[38:39], v[62:63], 0, v[36:37]
	v_lshl_add_u64 v[42:43], v[62:63], 0, v[42:43]
	v_lshl_add_u64 v[46:47], v[62:63], 0, v[44:45]
	v_lshl_add_u64 v[50:51], v[62:63], 0, v[50:51]
	v_lshl_add_u64 v[54:55], v[62:63], 0, v[52:53]
	v_lshl_add_u64 v[58:59], v[62:63], 0, v[58:59]
	v_lshl_add_u64 v[62:63], v[62:63], 0, v[60:61]
	global_load_dwordx4 v[26:29], v[30:31], off
	s_nop 0
	global_load_dwordx4 v[30:33], v[32:33], off
	s_nop 0
	global_load_dwordx4 v[34:37], v[34:35], off
	s_nop 0
	global_load_dwordx4 v[38:41], v[38:39], off
	s_nop 0
	global_load_dwordx4 v[42:45], v[42:43], off
	s_nop 0
	global_load_dwordx4 v[46:49], v[46:47], off
	s_nop 0
	global_load_dwordx4 v[50:53], v[50:51], off
	s_nop 0
	global_load_dwordx4 v[54:57], v[54:55], off
	s_nop 0
	global_load_dwordx4 v[58:61], v[58:59], off
	s_nop 0
	global_load_dwordx4 v[62:65], v[62:63], off
	s_waitcnt lgkmcnt(0)
	v_max_f32_e32 v68, v68, v68
	v_max_f32_e32 v66, v66, v68
	ds_bpermute_b32 v68, v223, v66
	ds_bpermute_b32 v77, v199, v69
	s_waitcnt lgkmcnt(0)
	s_barrier
; #define LAS __attribute__((address_space(3)))
; __device__ __forceinline__ void attn_unit(const AttnP& P, LAS unsigned char* lds, int b, int hd, int qq, int wave, int lane) {
;     ...
;     { const float mq = wave_max(fabsf(P.gq[lane])), mk = wave_max(fabsf(P.gk[lane])); shift = fminf(8.0f * mq * mk * 1.4426950408889634f, 64.0f); shift = shift > 30.0f ? shift : 0.f; }
;     {
;         u32x4 kr[8], vr[8];
; #pragma unroll
;         for (int j = 0; j < 8; ++j) { const int chunk = tid + 512 * j, row = chunk >> 3, piece = chunk & 7, cls = row >> 5, il = row & 31;
;             kr[j] = *(const u32x4*)(P.K + ((size_t)(hb * 16 + cls) * 128 + 32 * qq + il) * 64 + piece * 8); }
; #pragma unroll
;         for (int j = 0; j < 8; ++j) { const int chunk = tid + 512 * j, cls = chunk >> 8, within = chunk & 255;
;             vr[j] = *(const u32x4*)(P.Vt + ((size_t)(hb * 16 + cls) * 16 + 4 * qq) * 512 + within * 8); }
;         __syncthreads();
; #pragma unroll
;         for (int j = 0; j < 8; ++j) { const int chunk = tid + 512 * j, row = chunk >> 3, piece = chunk & 7;
;             *(LAS u32x4*)(lds + LDS_KC + row * KC_PITCH + piece * 16) = kr[j]; }
; #pragma unroll
;         for (int j = 0; j < 8; ++j) { const int chunk = tid + 512 * j; *(LAS u32x4*)(lds + LDS_VC + chunk * 16) = vr[j]; }
;     }
;     __syncthreads();
	v_max_f32_e32 v68, v68, v68
	v_max_f32_e32 v66, v66, v68
	ds_bpermute_b32 v68, v199, v66
	v_max_f32_e32 v77, v77, v77
	v_max_f32_e32 v69, v69, v77
	v_cndmask_b32_e32 v77, v215, v221, vcc
	v_lshlrev_b32_e32 v226, 2, v77
	ds_bpermute_b32 v77, v226, v69
	s_waitcnt lgkmcnt(1)
	v_max_f32_e32 v68, v68, v68
	v_max_f32_e32 v66, v66, v68
	ds_bpermute_b32 v68, v226, v66
	v_cmp_lt_i32_e32 vcc, v222, v216
	s_waitcnt lgkmcnt(1)
	v_max_f32_e32 v77, v77, v77
	v_max_f32_e32 v69, v69, v77
	v_cndmask_b32_e32 v77, v215, v222, vcc
	v_lshlrev_b32_e32 v227, 2, v77
	s_waitcnt lgkmcnt(0)
	v_max_f32_e32 v68, v68, v68
	ds_bpermute_b32 v77, v227, v69
	v_max_f32_e32 v66, v66, v68
	ds_bpermute_b32 v68, v227, v66
	s_add_i32 s58, s99, s92
	s_lshl_b64 s[6:7], s[58:59], 7
	s_waitcnt lgkmcnt(1)
	v_max_f32_e32 v77, v77, v77
	v_max_f32_e32 v69, v69, v77
	s_waitcnt lgkmcnt(0)
	v_max_f32_e32 v68, v68, v68
	v_max_f32_e32 v66, v66, v68
	v_mul_f32_e32 v68, 0x41000000, v69
	v_mul_f32_e32 v66, v68, v66
	v_mul_f32_e32 v77, 0x3fb8aa3b, v66
	v_add_u32_e32 v66, 0, v190
	v_mad_u64_u32 v[68:69], s[4:5], v1, s71, v[66:67]
	v_lshrrev_b32_e32 v1, 3, v70
	s_waitcnt vmcnt(15)
	ds_write_b128 v68, v[2:5]
	v_mad_u64_u32 v[2:3], s[4:5], v1, s71, v[66:67]
	v_lshrrev_b32_e32 v1, 3, v71
	s_waitcnt vmcnt(14)
	ds_write_b128 v2, v[6:9]
	v_mad_u64_u32 v[2:3], s[4:5], v1, s71, v[66:67]
	v_lshrrev_b32_e32 v1, 3, v72
	s_waitcnt vmcnt(13)
	ds_write_b128 v2, v[10:13]
	v_mad_u64_u32 v[2:3], s[4:5], v1, s71, v[66:67]
	v_lshrrev_b32_e32 v1, 3, v73
	s_waitcnt vmcnt(12)
	ds_write_b128 v2, v[14:17]
	v_mad_u64_u32 v[2:3], s[4:5], v1, s71, v[66:67]
	v_lshrrev_b32_e32 v1, 3, v74
	s_waitcnt vmcnt(11)
	ds_write_b128 v2, v[18:21]
	v_mad_u64_u32 v[2:3], s[4:5], v1, s71, v[66:67]
	v_lshrrev_b32_e32 v1, 3, v75
	s_waitcnt vmcnt(10)
	ds_write_b128 v2, v[22:25]
	v_mad_u64_u32 v[2:3], s[4:5], v1, s71, v[66:67]
	v_lshrrev_b32_e32 v1, 3, v76
	s_lshl_b32 s13, s1, 5
	v_mov_b32_e32 v5, s7
	s_add_i32 s14, s12, 1
	s_lshl_b32 s19, s1, 2
	s_lshl_b32 s1, s14, 5
	s_or_b32 s22, s1, 0xffffff80
	s_lshl_b32 s20, s0, 8
	v_mov_b64_e32 v[156:157], v[84:85]
	s_add_i32 s21, s19, -4
	v_mov_b64_e32 v[154:155], v[82:83]
	s_waitcnt vmcnt(9)
	ds_write_b128 v2, v[26:29]
	v_mad_u64_u32 v[2:3], s[4:5], v1, s71, v[66:67]
	v_add_u32_e32 v1, s93, v67
	s_waitcnt vmcnt(8)
	ds_write_b128 v2, v[30:33]
	s_waitcnt vmcnt(7)
	ds_write_b128 v1, v[34:37]
	s_waitcnt vmcnt(6)
	ds_write_b128 v1, v[38:41] offset:8192
	s_waitcnt vmcnt(5)
	ds_write_b128 v1, v[42:45] offset:16384
	s_waitcnt vmcnt(4)
	ds_write_b128 v1, v[46:49] offset:24576
	s_waitcnt vmcnt(3)
	ds_write_b128 v1, v[50:53] offset:32768
	s_waitcnt vmcnt(2)
	ds_write_b128 v1, v[54:57] offset:40960
	s_waitcnt vmcnt(1)
	ds_write_b128 v1, v[58:61] offset:49152
	s_waitcnt vmcnt(0)
	ds_write_b128 v1, v[62:65] offset:57344
	v_min_f32_e32 v1, 0x42800000, v77
	v_cmp_lt_f32_e32 vcc, s30, v1
	s_waitcnt lgkmcnt(0)
	s_barrier
; #define LAS __attribute__((address_space(3)))
; __device__ __forceinline__ void tile_compute(const bf16x8 (&kf)[4], const bf16x8 (&vf)[2][2], const bf16x8 (&qf)[4], unsigned long long w0, unsigned long long w1,
;                                              float shift, f32x16& o0, f32x16& o1, f32x16& zacc, const bf16x8& ones) {
;     ...
;     for (int eg = 0; eg < 2; ++eg) {
;         const unsigned long long w = eg ? w1 : w0;
;         const unsigned wl = (unsigned)w, wh = (unsigned)(w >> 32);
;         float pv[8];
; #pragma unroll
;         for (int p = 0; p < 4; ++p) {
;             pv[p] = (float)((wl >> (8 * p)) & 0xffu) * __builtin_amdgcn_exp2f(st[8 * eg + p]);
;             pv[4 + p] = (float)((wh >> (8 * p)) & 0xffu) * __builtin_amdgcn_exp2f(st[8 * eg + 4 + p]);
;         }
; #pragma unroll
;         for (int p = 0; p < 4; ++p) pw[4 * eg + p] = pk2(pv[2 * p], pv[2 * p + 1]);
;     }
;     const bf16x8 pf0 = __builtin_bit_cast(bf16x8, (u32x4){pw[0], pw[1], pw[2], pw[3]});
;     const bf16x8 pf1 = __builtin_bit_cast(bf16x8, (u32x4){pw[4], pw[5], pw[6], pw[7]});
;     o0 = __builtin_amdgcn_mfma_f32_32x32x16_bf16(vf[0][0], pf0, o0, 0, 0, 0);
; __device__ __forceinline__ void attn_task(const AttnP& P, LAS unsigned char* lds, int b, int hd, int qq, int c, float shift, int lane_in) {
;     ...
;     const int hb = b * 8 + hd, q = lane & 31, h = lane >> 5, R0 = 4 * qq, iq0 = 32 * qq;
;     bf16x8 qf[4];
;     { const bf16_t* qp = P.Q + ((size_t)(hb * 16 + c) * 128 + iq0 + q) * 64 + 8 * h;
; #pragma unroll
;       for (int kk = 0; kk < 4; ++kk) qf[kk] = *(const bf16x8*)(qp + 16 * kk); }
;     bf16x8 gk[4];
;     int gi = next_tile(0, R0);
;     if (gi < 10) attn_load_k(P, lds, hb, gi, c, R0, lane, gk);
;     unsigned long long Hp[2], Hn[2], Bp[2], Bn[2], mT0[2], mT3[2], mAp[2], mAn[2], mLp, mLn;
;     { const LAS unsigned long long* T = (const LAS unsigned long long*)(lds + LDS_ATAB + lane * 144);
;       Hp[0] = T[0]; Hp[1] = T[1]; Hn[0] = T[2]; Hn[1] = T[3]; Bp[0] = T[4]; Bp[1] = T[5]; Bn[0] = T[6]; Bn[1] = T[7];
;       mT0[0] = T[8]; mT0[1] = T[9]; mT3[0] = T[10]; mT3[1] = T[11]; mAp[0] = T[12]; mAp[1] = T[13]; mAn[0] = T[14]; mAn[1] = T[15]; mLp = T[16]; mLn = T[17]; }
;     f32x16 o0 = {}, o1 = {}, zacc = {};
;     bf16x8 ones = {0x3F80, 0x3F80, 0x3F80, 0x3F80, 0x3F80, 0x3F80, 0x3F80, 0x3F80}; asm volatile("" : "+v"(ones));
;     int li = 10, ph = 0;
	v_cndmask_b32_e32 v2, 0, v1, vcc
	v_and_b32_e32 v229, 31, v228
	v_ashrrev_i32_e32 v17, 5, v228
	v_or_b32_e32 v1, s6, v229
	v_or_b32_e32 v4, s13, v1
	v_lshlrev_b32_e32 v6, 3, v17
	v_lshlrev_b64 v[4:5], 7, v[4:5]
	v_ashrrev_i32_e32 v7, 31, v6
	v_lshl_add_u64 v[4:5], s[46:47], 0, v[4:5]
	v_lshlrev_b64 v[6:7], 1, v[6:7]
	v_lshl_add_u64 v[4:5], v[4:5], 0, v[6:7]
	v_lshrrev_b32_e32 v1, 3, v228
	v_bfe_u32 v3, v228, 2, 1
	global_load_dwordx4 v[86:89], v[4:5], off
	global_load_dwordx4 v[90:93], v[4:5], off offset:32
	global_load_dwordx4 v[94:97], v[4:5], off offset:64
	global_load_dwordx4 v[98:101], v[4:5], off offset:96
	v_and_or_b32 v1, v1, 2, v3
	v_lshrrev_b32_e32 v3, 1, v228
	v_and_b32_e32 v4, 3, v228
	v_and_or_b32 v198, v3, 4, v4
	v_or_b32_e32 v3, s19, v1
	v_lshl_add_u32 v4, v3, 3, s22
	v_ashrrev_i32_e32 v5, 31, v4
	v_lshl_add_u64 v[4:5], s[6:7], 0, v[4:5]
	v_or_b32_e32 v4, v4, v198
	v_lshlrev_b64 v[4:5], 7, v[4:5]
	v_lshl_add_u64 v[4:5], s[50:51], 0, v[4:5]
	v_lshl_add_u64 v[4:5], v[4:5], 0, v[6:7]
	global_load_dwordx4 v[110:113], v[4:5], off
	global_load_dwordx4 v[126:129], v[4:5], off offset:32
	global_load_dwordx4 v[130:133], v[4:5], off offset:64
	global_load_dwordx4 v[106:109], v[4:5], off offset:96
	v_mul_lo_u32 v4, v228, s31
	v_add_u32_e32 v4, 0, v4
	v_add_u32_e32 v4, 0x24000, v4
	ds_read_b128 v[102:105], v4
	ds_read_b128 v[114:117], v4 offset:16
	ds_read_b128 v[118:121], v4 offset:32
	ds_read_b128 v[122:125], v4 offset:48
	ds_read_b128 v[134:137], v4 offset:64
	ds_read_b128 v[138:141], v4 offset:80
	ds_read_b128 v[142:145], v4 offset:96
	ds_read_b128 v[146:149], v4 offset:112
	ds_read_b128 v[150:153], v4 offset:128
	s_waitcnt lgkmcnt(8)
	v_mad_u64_u32 v[4:5], s[0:1], v102, 3, 0
	v_mov_b32_e32 v8, v5
	v_mad_u64_u32 v[8:9], s[0:1], v103, 3, v[8:9]
	s_waitcnt lgkmcnt(7)
	v_sub_co_u32_e32 v4, vcc, v4, v114
	v_lshlrev_b32_e32 v10, 3, v1
	s_nop 0
	v_subb_co_u32_e32 v5, vcc, v8, v115, vcc
	s_waitcnt lgkmcnt(5)
	v_lshl_add_u64 v[202:203], v[4:5], 0, v[122:123]
	v_mad_u64_u32 v[4:5], s[0:1], v104, 3, 0
	v_mov_b32_e32 v8, v5
	v_mad_u64_u32 v[8:9], s[0:1], v105, 3, v[8:9]
	v_sub_co_u32_e32 v4, vcc, v4, v116
	v_lshlrev_b32_e32 v190, 4, v229
	v_add_u32_e32 v235, 2, v17
	v_subb_co_u32_e32 v5, vcc, v8, v117, vcc
	v_lshl_add_u32 v200, v17, 4, 0
	v_or_b32_e32 v230, 0xffffffe4, v1
	s_add_i32 s15, s19, -1
	v_or_b32_e32 v231, s21, v1
	v_or_b32_e32 v232, -16, v3
	v_add_u32_e32 v233, s93, v190
	s_or_b32 s16, s19, -16
	v_add_u32_e32 v234, s21, v17
	v_add_u32_e32 v236, s21, v235
	v_lshl_add_u64 v[204:205], v[4:5], 0, v[124:125]
	v_subrev_u32_e32 v237, 26, v17
	v_lshl_add_u32 v238, v17, 10, v214
	v_lshl_add_u64 v[206:207], s[50:51], 0, v[6:7]
	v_lshl_add_u64 v[208:209], s[52:53], 0, v[190:191]
	v_or3_b32 v239, v198, v10, s36
	s_sub_i32 s17, 16, s19
	v_mov_b32_e32 v1, v2
	v_mov_b32_e32 v4, v2
	v_mov_b32_e32 v3, v2
	v_mov_b32_e32 v6, v2
	s_mov_b64 s[0:1], -1
	s_mov_b32 s23, s14
	s_mov_b32 s24, 10
	s_mov_b32 s10, 0
	v_mov_b32_e32 v18, v191
	v_mov_b32_e32 v19, v191
	v_mov_b32_e32 v20, v191
	v_mov_b32_e32 v21, v191
	v_mov_b32_e32 v22, v191
	v_mov_b32_e32 v23, v191
	v_mov_b32_e32 v24, v191
	v_mov_b32_e32 v25, v191
	v_mov_b32_e32 v26, v191
	v_mov_b32_e32 v27, v191
	v_mov_b32_e32 v28, v191
	v_mov_b32_e32 v29, v191
	v_mov_b32_e32 v30, v191
	v_mov_b32_e32 v31, v191
	v_mov_b32_e32 v32, v191
	v_mov_b32_e32 v33, v191
	v_mov_b32_e32 v34, v191
	v_mov_b32_e32 v35, v191
	v_mov_b32_e32 v36, v191
	v_mov_b32_e32 v37, v191
	v_mov_b32_e32 v38, v191
	v_mov_b32_e32 v39, v191
	v_mov_b32_e32 v40, v191
	v_mov_b32_e32 v41, v191
	v_mov_b32_e32 v42, v191
	v_mov_b32_e32 v43, v191
	v_mov_b32_e32 v44, v191
	v_mov_b32_e32 v45, v191
	v_mov_b32_e32 v46, v191
	v_mov_b32_e32 v47, v191
	v_mov_b32_e32 v48, v191
	v_mov_b32_e32 v49, v191
	v_mov_b32_e32 v50, v191
	v_mov_b32_e32 v51, v191
	v_mov_b32_e32 v52, v191
	v_mov_b32_e32 v53, v191
	v_mov_b32_e32 v54, v191
	v_mov_b32_e32 v55, v191
	v_mov_b32_e32 v56, v191
	v_mov_b32_e32 v57, v191
	v_mov_b32_e32 v58, v191
	v_mov_b32_e32 v59, v191
	v_mov_b32_e32 v60, v191
	v_mov_b32_e32 v61, v191
	v_mov_b32_e32 v62, v191
	v_mov_b32_e32 v63, v191
	v_mov_b32_e32 v64, v191
	v_mov_b32_e32 v65, v191
	v_mov_b32_e32 v5, v2
	v_mov_b32_e32 v8, v2
	v_mov_b32_e32 v7, v2
	v_mov_b32_e32 v10, v2
	v_mov_b32_e32 v9, v2
	v_mov_b32_e32 v12, v2
	v_mov_b32_e32 v11, v2
	v_mov_b32_e32 v14, v2
	v_mov_b32_e32 v13, v2
	v_mov_b32_e32 v16, v2
	v_mov_b32_e32 v15, v2
	s_waitcnt vmcnt(4)
	s_branch .LBB0_171
.LBB0_170:
	s_nop 5
	v_exp_f32_e32 v66, v66
	s_nop 3
	v_exp_f32_e32 v67, v67
	v_exp_f32_e32 v70, v70
	v_exp_f32_e32 v71, v71
	v_exp_f32_e32 v68, v68
	v_exp_f32_e32 v69, v69
	v_cvt_f32_ubyte1_e32 v175, v212
	v_cvt_f32_ubyte0_e32 v174, v212
	v_exp_f32_e32 v72, v72
	v_exp_f32_e32 v73, v73
	v_pk_mul_f32 v[66:67], v[66:67], v[174:175]
	v_cvt_f32_ubyte1_e32 v175, v213
	v_cvt_f32_ubyte0_e32 v174, v213
	v_pk_mul_f32 v[70:71], v[70:71], v[174:175]
	v_cvt_f32_ubyte3_e32 v175, v212
	v_cvt_f32_ubyte2_e32 v174, v212
	v_pk_mul_f32 v[68:69], v[68:69], v[174:175]
	v_cvt_f32_ubyte3_e32 v175, v213
	v_cvt_f32_ubyte2_e32 v174, v213
	v_pk_mul_f32 v[72:73], v[72:73], v[174:175]
	v_cvt_pk_bf16_f32 v66, v66, v67
	v_cvt_pk_bf16_f32 v67, v68, v69
	v_cvt_pk_bf16_f32 v68, v70, v71
	v_exp_f32_e32 v70, v74
	v_exp_f32_e32 v71, v75
	v_cvt_pk_bf16_f32 v69, v72, v73
	v_exp_f32_e32 v72, v78
	v_exp_f32_e32 v73, v79
	s_waitcnt vmcnt(4)
	v_mfma_f32_32x32x16_bf16 v[18:33], v[162:165], v[66:69], v[18:33]
	v_cvt_f32_ubyte1_e32 v75, v210
	v_cvt_f32_ubyte0_e32 v74, v210
	v_mul_f32_e64 v70, v70, v74
	v_mul_f32_e64 v71, v71, v75
	v_cvt_f32_ubyte1_e32 v75, v211
	v_cvt_f32_ubyte0_e32 v74, v211
	v_pk_mul_f32 v[72:73], v[72:73], v[74:75]
	v_exp_f32_e32 v74, v76
	v_mfma_f32_32x32x16_bf16 v[34:49], v[158:161], v[66:69], v[34:49]
	v_exp_f32_e32 v75, v77
	v_exp_f32_e32 v76, v80
	v_exp_f32_e32 v77, v81
	v_cvt_f32_ubyte3_e32 v79, v210
	v_cvt_f32_ubyte2_e32 v78, v210
	v_pk_mul_f32 v[74:75], v[74:75], v[78:79]
	s_cmp_lt_i32 s24, 26
	v_mfma_f32_32x32x16_bf16 v[50:65], v[154:157], v[66:69], v[50:65]
	v_cvt_f32_ubyte3_e32 v67, v211
	v_cvt_f32_ubyte2_e32 v66, v211
	v_mul_f32_e64 v76, v76, v66
	v_mul_f32_e64 v77, v77, v67
	v_cvt_pk_bf16_f32 v66, v70, v71
	v_cvt_pk_bf16_f32 v67, v74, v75
	v_cvt_pk_bf16_f32 v68, v72, v73
	v_cvt_pk_bf16_f32 v69, v76, v77
	s_cselect_b64 s[4:5], -1, 0
	s_cmp_lt_i32 s23, 10
	v_mfma_f32_32x32x16_bf16 v[18:33], v[166:169], v[66:69], v[18:33]
	s_cselect_b64 s[0:1], -1, 0
	s_or_b64 s[4:5], s[4:5], s[0:1]
	s_and_b64 vcc, exec, s[4:5]
	v_mfma_f32_32x32x16_bf16 v[34:49], v[170:173], v[66:69], v[34:49]
	v_mfma_f32_32x32x16_bf16 v[50:65], v[154:157], v[66:69], v[50:65]
	s_cbranch_vccz .LBB0_247

; __device__ __forceinline__ void attn_task(const AttnP& P, LAS unsigned char* lds, int b, int hd, int qq, int c, float shift, int lane_in) {
;     ...
;         if (gi < 10 && (ph >= 2 || li >= 26)) {
;             attn_load_v(P, lds, hb, gi, c, R0, lane, vf);
; #pragma unroll
;             for (int kk = 0; kk < 4; ++kk) kf[kk] = gk[kk];
;             if (gi < 4) {
;                 if (gi == 0) { w0 = mT0[0]; w1 = mT0[1]; } else if (gi == 3) { w0 = mT3[0]; w1 = mT3[1]; } else { w0 = 0x0101010101010101ull; w1 = 0x0101010101010101ull; }
;             } else if (gi < 7) {
;                 const bool pos = c > ((c + 4 * (gi - 3)) & 15);
;                 w0 = pos ? mAp[0] : mAn[0]; w1 = pos ? mAp[1] : mAn[1];
;             } else {
;                 { int cg, Rg; run_desc(gi, h, c, R0, cg, Rg); w0 = (c > cg) ? mLp : mLn; }
;                 { int cg, Rg; run_desc(gi, 2 + h, c, R0, cg, Rg); w1 = (c > cg) ? mLp : mLn; }
;             }
.LBB0_178:
	s_and_b64 vcc, exec, s[0:1]
	s_cbranch_vccz .LBB0_244
	s_cmp_gt_i32 s23, 3
	s_cselect_b64 s[8:9], -1, 0
	s_lshl_b32 s25, s23, 2
	s_sub_i32 s27, s25, 28
	s_cmp_gt_u32 s23, 6
	s_cselect_b64 s[0:1], -1, 0
	s_add_i32 s4, s25, s63
	s_waitcnt lgkmcnt(3)
	v_cndmask_b32_e64 v66, 0, 1, s[0:1]
	s_and_b32 s26, s4, 15
	s_mov_b64 s[10:11], -1
	s_and_b64 vcc, exec, s[8:9]
	v_cmp_ne_u32_e64 s[4:5], 1, v66
	s_cbranch_vccz .LBB0_183
	s_and_b64 vcc, exec, s[4:5]
	v_mov_b32_e32 v67, s26
	v_mov_b32_e32 v66, v234
	s_cbranch_vccnz .LBB0_182
	v_add_u32_e32 v66, s27, v17
	v_mul_lo_u32 v67, v66, 11
	v_lshrrev_b32_e32 v67, 5, v67
	v_add3_u32 v66, v66, s62, v67
	v_and_b32_e32 v67, 15, v66
	v_mov_b32_e32 v66, s15

; __device__ __forceinline__ int next_tile(int tt, int R0) { while (tt < 26 && !tile_valid(tt, R0)) ++tt; return tt; }
; __device__ __forceinline__ void attn_task(const AttnP& P, LAS unsigned char* lds, int b, int hd, int qq, int c, float shift, int lane_in) {
;     ...
;         if (gi < 10 && (ph >= 2 || li >= 26)) {
;             attn_load_v(P, lds, hb, gi, c, R0, lane, vf);
; #pragma unroll
;             for (int kk = 0; kk < 4; ++kk) kf[kk] = gk[kk];
;             if (gi < 4) {
;                 if (gi == 0) { w0 = mT0[0]; w1 = mT0[1]; } else if (gi == 3) { w0 = mT3[0]; w1 = mT3[1]; } else { w0 = 0x0101010101010101ull; w1 = 0x0101010101010101ull; }
;             } else if (gi < 7) {
;                 const bool pos = c > ((c + 4 * (gi - 3)) & 15);
;                 w0 = pos ? mAp[0] : mAn[0]; w1 = pos ? mAp[1] : mAn[1];
;             } else {
;                 { int cg, Rg; run_desc(gi, h, c, R0, cg, Rg); w0 = (c > cg) ? mLp : mLn; }
;                 { int cg, Rg; run_desc(gi, 2 + h, c, R0, cg, Rg); w1 = (c > cg) ? mLp : mLn; }
;             }
;             gi = next_tile(gi + 1, R0);
;             if (gi < 10) attn_load_k(P, lds, hb, gi, c, R0, lane, gk);
.LBB0_203:
	s_add_i32 s0, s25, 4
	s_max_i32 s0, s0, s17
	s_not_b32 s1, s25
	s_add_i32 s0, s0, s1
	s_max_i32 s1, s23, 3
	s_lshr_b32 s0, s0, 2
	s_sub_i32 s1, s1, s23
	s_min_u32 s0, s0, s1
	s_add_i32 s0, s23, s0
	s_add_i32 s23, s0, 1
	s_waitcnt vmcnt(4)
	v_mov_b64_e32 v[184:185], v[108:109]
	v_mov_b64_e32 v[182:183], v[106:107]
	v_mov_b64_e32 v[176:177], v[132:133]
	v_mov_b64_e32 v[174:175], v[130:131]
	v_mov_b64_e32 v[180:181], v[128:129]
	v_mov_b64_e32 v[178:179], v[126:127]
	v_mov_b64_e32 v[68:69], v[112:113]
	v_mov_b64_e32 v[66:67], v[110:111]
	s_cmp_gt_i32 s0, 8
	s_cbranch_scc1 .Lattn_nopf_1
	s_lshl_b32 s4, s23, 2
	s_cmp_gt_i32 s0, 2
	s_mov_b64 s[0:1], -1
	s_cbranch_scc0 .LBB0_210
	s_cmp_gt_u32 s23, 6
	s_cbranch_scc0 .LBB0_207
	v_add_u32_e32 v70, s4, v230
	v_mul_lo_u32 v71, v70, 11
	v_lshrrev_b32_e32 v71, 5, v71
	v_add3_u32 v70, v70, s62, v71
	v_and_b32_e32 v70, 15, v70
	s_mov_b64 s[0:1], 0
.LBB0_207:
	s_andn2_b64 vcc, exec, s[0:1]
	v_mov_b32_e32 v71, s15
	s_cbranch_vccnz .LBB0_209
	s_add_i32 s0, s4, s63
	s_and_b32 s0, s0, 15
	v_mov_b32_e32 v70, s0
	v_mov_b32_e32 v71, v231

; #define LAS __attribute__((address_space(3)))
; __device__ __forceinline__ void attn_load_k(const AttnP& P, LAS unsigned char* lds, int hb, int tt, int c, int R0, int lane, bf16x8 (&kf)[4]) {
;     const int rho = lane & 31, h = lane >> 5;
;     const int gk_ = 2 * (rho >> 4) + ((rho >> 2) & 1), pk_ = 4 * ((rho >> 3) & 1) + (rho & 3);
;     if (tt < 10) {
;         int cg, Rg; run_desc(tt, gk_, c, R0, cg, Rg);
;         const bf16_t* kp = P.K + ((size_t)(hb * 16 + cg) * 128 + 8 * Rg + pk_) * 64 + 8 * h;
; #pragma unroll
;         for (int kk = 0; kk < 4; ++kk) kf[kk] = *(const bf16x8*)(kp + 16 * kk);
.LBB0_210:
	s_andn2_b64 vcc, exec, s[0:1]
	s_cbranch_vccnz .LBB0_212
	v_add_u32_e32 v71, s4, v232
	v_mov_b32_e32 v70, s92
.LBB0_212:
	v_add_u32_e32 v190, s99, v70
	v_lshlrev_b32_e32 v70, 3, v71
	v_lshlrev_b64 v[72:73], 7, v[190:191]
	v_ashrrev_i32_e32 v71, 31, v70
	v_lshl_add_u64 v[70:71], v[72:73], 0, v[70:71]
	v_or_b32_e32 v70, v70, v198
	v_lshlrev_b64 v[70:71], 7, v[70:71]
	v_lshl_add_u64 v[70:71], v[206:207], 0, v[70:71]
	global_load_dwordx4 v[110:113], v[70:71], off
	global_load_dwordx4 v[126:129], v[70:71], off offset:32
	global_load_dwordx4 v[130:133], v[70:71], off offset:64
	global_load_dwordx4 v[106:109], v[70:71], off offset:96
	s_branch .Lattn_join_1

; __device__ __forceinline__ void attn_task(const AttnP& P, LAS unsigned char* lds, int b, int hd, int qq, int c, float shift, int lane_in) {
;     ...
;             if (gi < 10) attn_load_k(P, lds, hb, gi, c, R0, lane, gk);
;             ph = 0;
.Lattn_join_1:
.LBB0_213:
	s_mov_b32 s10, 0
	s_branch .LBB0_245

; __device__ __forceinline__ void tile_compute(const bf16x8 (&kf)[4], const bf16x8 (&vf)[2][2], const bf16x8 (&qf)[4], unsigned long long w0, unsigned long long w1,
;                                              float shift, f32x16& o0, f32x16& o1, f32x16& zacc, const bf16x8& ones) {
;     f32x16 st = {};
; #pragma unroll
;     for (int kk = 0; kk < 4; ++kk) st = __builtin_amdgcn_mfma_f32_32x32x16_bf16(kf[kk], qf[kk], st, 0, 0, 0);
;     if (__builtin_amdgcn_readfirstlane(__builtin_bit_cast(int, shift)) != 0) {
;         asm volatile("" ::: "memory");
; #pragma unroll
;         for (int e = 0; e < 16; ++e) st[e] -= shift;
;     }
.LBB0_245:
	s_waitcnt lgkmcnt(3)
	v_mfma_f32_32x32x16_bf16 v[66:81], v[66:69], v[86:89], 0
	v_readfirstlane_b32 s0, v2
	s_nop 1
	v_cmp_class_f32_e64 s[0:1], s0, 64
	s_and_b64 vcc, exec, s[0:1]
	s_waitcnt lgkmcnt(2)
	v_mfma_f32_32x32x16_bf16 v[66:81], v[178:181], v[90:93], v[66:81]
	s_waitcnt lgkmcnt(1)
	v_mfma_f32_32x32x16_bf16 v[66:81], v[174:177], v[94:97], v[66:81]
	s_waitcnt lgkmcnt(0)
	v_mfma_f32_32x32x16_bf16 v[66:81], v[182:185], v[98:101], v[66:81]
	s_cbranch_vccnz .LBB0_170
	s_nop 10
	v_sub_f32_e32 v81, v81, v15
	v_sub_f32_e32 v80, v80, v16
	v_sub_f32_e32 v79, v79, v13
	v_sub_f32_e32 v78, v78, v14
	v_sub_f32_e32 v77, v77, v11
	v_sub_f32_e32 v76, v76, v12
	v_sub_f32_e32 v75, v75, v9
	v_sub_f32_e32 v74, v74, v10
	v_sub_f32_e32 v73, v73, v7
	v_sub_f32_e32 v72, v72, v8
	v_sub_f32_e32 v71, v71, v5
	v_sub_f32_e32 v70, v70, v6
	v_sub_f32_e32 v69, v69, v3
	v_sub_f32_e32 v68, v68, v4
	v_sub_f32_e32 v67, v67, v1
	v_sub_f32_e32 v66, v66, v2
	s_branch .LBB0_170

; #define LAS __attribute__((address_space(3)))
; __device__ __forceinline__ unsigned pk2(float lo, float hi) { f32x2 v = {lo, hi}; bf16x2_t b = __builtin_convertvector(v, bf16x2_t); return __builtin_bit_cast(unsigned, b); }
; __device__ __forceinline__ int next_tile(int tt, int R0) { while (tt < 26 && !tile_valid(tt, R0)) ++tt; return tt; }
; __device__ __forceinline__ void attn_task(const AttnP& P, LAS unsigned char* lds, int b, int hd, int qq, int c, float shift, int lane_in) {
;     ...
;     const int hb = b * 8 + hd, q = lane & 31, h = lane >> 5, R0 = 4 * qq, iq0 = 32 * qq;
;     bf16x8 qf[4];
;     { const bf16_t* qp = P.Q + ((size_t)(hb * 16 + c) * 128 + iq0 + q) * 64 + 8 * h;
; #pragma unroll
;       for (int kk = 0; kk < 4; ++kk) qf[kk] = *(const bf16x8*)(qp + 16 * kk); }
;     bf16x8 gk[4];
;     int gi = next_tile(0, R0);
;     if (gi < 10) attn_load_k(P, lds, hb, gi, c, R0, lane, gk);
;     unsigned long long Hp[2], Hn[2], Bp[2], Bn[2], mT0[2], mT3[2], mAp[2], mAn[2], mLp, mLn;
;     { const LAS unsigned long long* T = (const LAS unsigned long long*)(lds + LDS_ATAB + lane * 144);
;       Hp[0] = T[0]; Hp[1] = T[1]; Hn[0] = T[2]; Hn[1] = T[3]; Bp[0] = T[4]; Bp[1] = T[5]; Bn[0] = T[6]; Bn[1] = T[7];
;       mT0[0] = T[8]; mT0[1] = T[9]; mT3[0] = T[10]; mT3[1] = T[11]; mAp[0] = T[12]; mAp[1] = T[13]; mAn[0] = T[14]; mAn[1] = T[15]; mLp = T[16]; mLn = T[17]; }
;     f32x16 o0 = {}, o1 = {}, zacc = {};
;     bf16x8 ones = {0x3F80, 0x3F80, 0x3F80, 0x3F80, 0x3F80, 0x3F80, 0x3F80, 0x3F80}; asm volatile("" : "+v"(ones));
;     int li = 10, ph = 0;
;     ...
;     const float rz = __builtin_amdgcn_rcpf(zacc[0]);
;     float ss = 0.f;
; #pragma unroll
;     for (int e = 0; e < 16; ++e) { o0[e] *= rz; o1[e] *= rz; ss += o0[e] * o0[e] + o1[e] * o1[e]; }
;     ss = xor32_sum(ss);
;     const size_t tok = (size_t)b * SEQ + c + 16 * (iq0 + q);
;     if (h == 0) P.ssqA[tok * 8 + hd] = ss;
;     bf16_t* orow = P.MIX + tok * DM + hd * 64;
; #pragma unroll
;     for (int e4 = 0; e4 < 4; ++e4) {
;         const int d0 = 8 * e4 + 4 * h;
;         u32x2 w0, w1;
;         w0.x = pk2(o0[4 * e4], o0[4 * e4 + 1]); w0.y = pk2(o0[4 * e4 + 2], o0[4 * e4 + 3]);
;         w1.x = pk2(o1[4 * e4], o1[4 * e4 + 1]); w1.y = pk2(o1[4 * e4 + 2], o1[4 * e4 + 3]);
;         *(u32x2*)(orow + d0) = w0; *(u32x2*)(orow + 32 + d0) = w1;
;     }
.LBB0_249:
	s_or_b64 exec, exec, s[0:1]
	v_readlane_b32 s0, v243, 20
	v_lshlrev_b64 v[48:49], 11, v[190:191]
	v_readlane_b32 s1, v243, 21
	s_lshl_b32 s58, s98, 7
	v_lshlrev_b32_e32 v52, 2, v17
	v_lshl_add_u64 v[48:49], s[0:1], 0, v[48:49]
	v_lshl_add_u64 v[48:49], v[48:49], 0, s[58:59]
	v_ashrrev_i32_e32 v53, 31, v52
	v_cvt_pk_bf16_f32 v50, v50, v51
	v_cvt_pk_bf16_f32 v51, v34, v35
	v_cvt_pk_bf16_f32 v18, v18, v19
	v_cvt_pk_bf16_f32 v19, v20, v21
	v_lshl_add_u64 v[20:21], v[52:53], 1, v[48:49]
	global_store_dwordx2 v[20:21], v[50:51], off
	global_store_dwordx2 v[20:21], v[18:19], off offset:64
	v_cvt_pk_bf16_f32 v18, v36, v37
	v_cvt_pk_bf16_f32 v19, v38, v39
	v_cvt_pk_bf16_f32 v22, v22, v23
	v_cvt_pk_bf16_f32 v23, v24, v25
	global_store_dwordx2 v[20:21], v[18:19], off offset:16
	global_store_dwordx2 v[20:21], v[22:23], off offset:80
	v_cvt_pk_bf16_f32 v18, v40, v41
	v_cvt_pk_bf16_f32 v19, v42, v43
	v_cvt_pk_bf16_f32 v22, v26, v27
	v_cvt_pk_bf16_f32 v23, v28, v29
	global_store_dwordx2 v[20:21], v[18:19], off offset:32
	global_store_dwordx2 v[20:21], v[22:23], off offset:96
	v_cvt_pk_bf16_f32 v18, v44, v45
	v_cvt_pk_bf16_f32 v19, v46, v47
	v_mov_b32_e32 v229, v201
	s_add_i32 s58, s99, s64
	v_cvt_pk_bf16_f32 v22, v30, v31
	v_cvt_pk_bf16_f32 v23, v32, v33
	global_store_dwordx2 v[20:21], v[18:19], off offset:48
	global_store_dwordx2 v[20:21], v[22:23], off offset:112
	s_lshl_b64 s[26:27], s[58:59], 7
	v_and_b32_e32 v230, 31, v229
	v_ashrrev_i32_e32 v228, 5, v229
	v_or_b32_e32 v17, s26, v230
	v_mov_b32_e32 v19, s27
	v_or_b32_e32 v18, s13, v17
	v_lshlrev_b32_e32 v20, 3, v228
	v_lshlrev_b64 v[18:19], 7, v[18:19]
	v_ashrrev_i32_e32 v21, 31, v20
	v_lshl_add_u64 v[18:19], s[46:47], 0, v[18:19]
	v_lshlrev_b64 v[20:21], 1, v[20:21]
	v_lshl_add_u64 v[18:19], v[18:19], 0, v[20:21]
	global_load_dwordx4 v[86:89], v[18:19], off
	global_load_dwordx4 v[90:93], v[18:19], off offset:32
	global_load_dwordx4 v[94:97], v[18:19], off offset:64
	global_load_dwordx4 v[98:101], v[18:19], off offset:96
	v_lshrrev_b32_e32 v17, 3, v229
	v_bfe_u32 v18, v229, 2, 1
	v_and_or_b32 v22, v17, 2, v18
	v_lshrrev_b32_e32 v17, 1, v229
	v_and_b32_e32 v18, 3, v229
	v_or_b32_e32 v23, s19, v22
	v_and_or_b32 v198, v17, 4, v18
	v_lshl_add_u32 v18, v23, 3, s22
	v_ashrrev_i32_e32 v19, 31, v18
	v_lshl_add_u64 v[18:19], s[26:27], 0, v[18:19]
	v_or_b32_e32 v18, v18, v198
	v_lshlrev_b64 v[18:19], 7, v[18:19]
	v_lshl_add_u64 v[18:19], s[50:51], 0, v[18:19]
	v_lshl_add_u64 v[18:19], v[18:19], 0, v[20:21]
	global_load_dwordx4 v[110:113], v[18:19], off
	global_load_dwordx4 v[126:129], v[18:19], off offset:32
	global_load_dwordx4 v[130:133], v[18:19], off offset:64
	global_load_dwordx4 v[106:109], v[18:19], off offset:96
	v_mul_lo_u32 v17, v229, s31
	v_add_u32_e32 v17, 0, v17
	v_add_u32_e32 v17, 0x24000, v17
	ds_read_b128 v[102:105], v17
	ds_read_b128 v[114:117], v17 offset:16
	ds_read_b128 v[118:121], v17 offset:32
	ds_read_b128 v[122:125], v17 offset:48
	ds_read_b128 v[134:137], v17 offset:64
	ds_read_b128 v[138:141], v17 offset:80
	ds_read_b128 v[142:145], v17 offset:96
	ds_read_b128 v[146:149], v17 offset:112
	ds_read_b128 v[150:153], v17 offset:128
	s_waitcnt lgkmcnt(8)
	v_mad_u64_u32 v[18:19], s[0:1], v102, 3, 0
	v_lshlrev_b32_e32 v24, 3, v22
	v_or_b32_e32 v17, 0xffffffe4, v22
	v_or_b32_e32 v231, s21, v22
	v_mov_b32_e32 v22, v19
	v_or_b32_e32 v232, -16, v23
	v_mad_u64_u32 v[22:23], s[0:1], v103, 3, v[22:23]
	s_waitcnt lgkmcnt(7)
	v_sub_co_u32_e32 v18, vcc, v18, v114
	v_mov_b64_e32 v[156:157], v[84:85]
	s_nop 0
	v_subb_co_u32_e32 v19, vcc, v22, v115, vcc
	s_waitcnt lgkmcnt(5)
	v_lshl_add_u64 v[202:203], v[18:19], 0, v[122:123]
	v_mad_u64_u32 v[18:19], s[0:1], v104, 3, 0
	v_mov_b32_e32 v22, v19
	v_mad_u64_u32 v[22:23], s[0:1], v105, 3, v[22:23]
	v_sub_co_u32_e32 v18, vcc, v18, v116
	v_lshlrev_b32_e32 v190, 4, v230
	s_nop 0
	v_subb_co_u32_e32 v19, vcc, v22, v117, vcc
	v_add_u32_e32 v235, 2, v228
	v_lshl_add_u64 v[204:205], v[18:19], 0, v[124:125]
	v_mov_b32_e32 v18, 0
	s_lshl_b32 s23, s98, 6
	v_mov_b64_e32 v[154:155], v[82:83]
	v_lshl_add_u32 v200, v228, 4, 0
	v_add_u32_e32 v233, s93, v190
	v_add_u32_e32 v234, s21, v228
	v_add_u32_e32 v236, s21, v235
	v_subrev_u32_e32 v237, 26, v228
	s_mov_b32 s19, 10
	v_lshl_add_u32 v238, v228, 10, v214
	v_lshl_add_u64 v[206:207], s[50:51], 0, v[20:21]
	v_lshl_add_u64 v[208:209], s[52:53], 0, v[190:191]
	v_or3_b32 v239, v198, v24, s36
	s_mov_b32 s10, 0
	s_mov_b64 s[0:1], -1
	v_mov_b32_e32 v19, v18
	v_mov_b32_e32 v20, v18
	v_mov_b32_e32 v21, v18
	v_mov_b32_e32 v22, v18
	v_mov_b32_e32 v23, v18
	v_mov_b32_e32 v24, v18
	v_mov_b32_e32 v25, v18
	v_mov_b32_e32 v26, v18
	v_mov_b32_e32 v27, v18
	v_mov_b32_e32 v28, v18
	v_mov_b32_e32 v29, v18
	v_mov_b32_e32 v30, v18
	v_mov_b32_e32 v31, v18
	v_mov_b32_e32 v32, v18
	v_mov_b32_e32 v33, v18
	v_mov_b32_e32 v34, v18
	v_mov_b32_e32 v35, v18
	v_mov_b32_e32 v36, v18
	v_mov_b32_e32 v37, v18
	v_mov_b32_e32 v38, v18
	v_mov_b32_e32 v39, v18
	v_mov_b32_e32 v40, v18
	v_mov_b32_e32 v41, v18
	v_mov_b32_e32 v42, v18
	v_mov_b32_e32 v43, v18
	v_mov_b32_e32 v44, v18
	v_mov_b32_e32 v45, v18
	v_mov_b32_e32 v46, v18
	v_mov_b32_e32 v47, v18
	v_mov_b32_e32 v48, v18
	v_mov_b32_e32 v49, v18
	v_mov_b32_e32 v50, v18
	v_mov_b32_e32 v51, v18
	v_mov_b32_e32 v52, v18
	v_mov_b32_e32 v53, v18
	v_mov_b32_e32 v54, v18
	v_mov_b32_e32 v55, v18
	v_mov_b32_e32 v56, v18
	v_mov_b32_e32 v57, v18
	v_mov_b32_e32 v58, v18
	v_mov_b32_e32 v59, v18
	v_mov_b32_e32 v60, v18
	v_mov_b32_e32 v61, v18
	v_mov_b32_e32 v62, v18
	v_mov_b32_e32 v63, v18
	v_mov_b32_e32 v64, v18
	v_mov_b32_e32 v65, v18
	s_waitcnt vmcnt(4)
	s_branch .LBB0_251
; __device__ __forceinline__ unsigned pk2(float lo, float hi) { f32x2 v = {lo, hi}; bf16x2_t b = __builtin_convertvector(v, bf16x2_t); return __builtin_bit_cast(unsigned, b); }
; __device__ __forceinline__ void tile_compute(const bf16x8 (&kf)[4], const bf16x8 (&vf)[2][2], const bf16x8 (&qf)[4], unsigned long long w0, unsigned long long w1,
;                                              float shift, f32x16& o0, f32x16& o1, f32x16& zacc, const bf16x8& ones) {
;     ...
;     unsigned pw[8];
; #pragma unroll
;     for (int eg = 0; eg < 2; ++eg) {
;         const unsigned long long w = eg ? w1 : w0;
;         const unsigned wl = (unsigned)w, wh = (unsigned)(w >> 32);
;         float pv[8];
; #pragma unroll
;         for (int p = 0; p < 4; ++p) {
;             pv[p] = (float)((wl >> (8 * p)) & 0xffu) * __builtin_amdgcn_exp2f(st[8 * eg + p]);
;             pv[4 + p] = (float)((wh >> (8 * p)) & 0xffu) * __builtin_amdgcn_exp2f(st[8 * eg + 4 + p]);
;         }
; #pragma unroll
;         for (int p = 0; p < 4; ++p) pw[4 * eg + p] = pk2(pv[2 * p], pv[2 * p + 1]);
;     }
;     const bf16x8 pf0 = __builtin_bit_cast(bf16x8, (u32x4){pw[0], pw[1], pw[2], pw[3]});
;     const bf16x8 pf1 = __builtin_bit_cast(bf16x8, (u32x4){pw[4], pw[5], pw[6], pw[7]});
;     o0 = __builtin_amdgcn_mfma_f32_32x32x16_bf16(vf[0][0], pf0, o0, 0, 0, 0);
;     o1 = __builtin_amdgcn_mfma_f32_32x32x16_bf16(vf[1][0], pf0, o1, 0, 0, 0);
;     zacc = __builtin_amdgcn_mfma_f32_32x32x16_bf16(ones, pf0, zacc, 0, 0, 0);
;     o0 = __builtin_amdgcn_mfma_f32_32x32x16_bf16(vf[0][1], pf1, o0, 0, 0, 0);
;     o1 = __builtin_amdgcn_mfma_f32_32x32x16_bf16(vf[1][1], pf1, o1, 0, 0, 0);
;     zacc = __builtin_amdgcn_mfma_f32_32x32x16_bf16(ones, pf1, zacc, 0, 0, 0);
; }
.LBB0_250:
	s_nop 5
	v_exp_f32_e32 v66, v66
	s_nop 3
	v_exp_f32_e32 v67, v67
	v_exp_f32_e32 v70, v70
	v_exp_f32_e32 v71, v71
	v_exp_f32_e32 v68, v68
	v_exp_f32_e32 v69, v69
	v_cvt_f32_ubyte1_e32 v175, v212
	v_cvt_f32_ubyte0_e32 v174, v212
	v_exp_f32_e32 v72, v72
	v_exp_f32_e32 v73, v73
	v_pk_mul_f32 v[66:67], v[66:67], v[174:175]
	v_cvt_f32_ubyte1_e32 v175, v213
	v_cvt_f32_ubyte0_e32 v174, v213
	v_pk_mul_f32 v[70:71], v[70:71], v[174:175]
	v_cvt_f32_ubyte3_e32 v175, v212
	v_cvt_f32_ubyte2_e32 v174, v212
	v_pk_mul_f32 v[68:69], v[68:69], v[174:175]
	v_cvt_f32_ubyte3_e32 v175, v213
	v_cvt_f32_ubyte2_e32 v174, v213
	v_pk_mul_f32 v[72:73], v[72:73], v[174:175]
	v_cvt_pk_bf16_f32 v66, v66, v67
	v_cvt_pk_bf16_f32 v67, v68, v69
	v_cvt_pk_bf16_f32 v68, v70, v71
	v_exp_f32_e32 v70, v74
	v_exp_f32_e32 v71, v75
	v_cvt_pk_bf16_f32 v69, v72, v73
	v_exp_f32_e32 v72, v78
	v_exp_f32_e32 v73, v79
	s_waitcnt vmcnt(4)
	v_mfma_f32_32x32x16_bf16 v[18:33], v[162:165], v[66:69], v[18:33]
	v_cvt_f32_ubyte1_e32 v75, v210
	v_cvt_f32_ubyte0_e32 v74, v210
	v_mul_f32_e64 v70, v70, v74
	v_mul_f32_e64 v71, v71, v75
	v_cvt_f32_ubyte1_e32 v75, v211
	v_cvt_f32_ubyte0_e32 v74, v211
	v_pk_mul_f32 v[72:73], v[72:73], v[74:75]
	v_exp_f32_e32 v74, v76
	v_mfma_f32_32x32x16_bf16 v[34:49], v[158:161], v[66:69], v[34:49]
	v_exp_f32_e32 v75, v77
	v_exp_f32_e32 v76, v80
	v_exp_f32_e32 v77, v81
	v_cvt_f32_ubyte3_e32 v79, v210
	v_cvt_f32_ubyte2_e32 v78, v210
	v_pk_mul_f32 v[74:75], v[74:75], v[78:79]
	s_cmp_lt_i32 s19, 26
	v_mfma_f32_32x32x16_bf16 v[50:65], v[154:157], v[66:69], v[50:65]
	v_cvt_f32_ubyte3_e32 v67, v211
	v_cvt_f32_ubyte2_e32 v66, v211
	v_mul_f32_e64 v76, v76, v66
	v_mul_f32_e64 v77, v77, v67
	v_cvt_pk_bf16_f32 v66, v70, v71
	v_cvt_pk_bf16_f32 v67, v74, v75
	v_cvt_pk_bf16_f32 v68, v72, v73
	v_cvt_pk_bf16_f32 v69, v76, v77
	s_cselect_b64 s[4:5], -1, 0
	s_cmp_lt_i32 s14, 10
	v_mfma_f32_32x32x16_bf16 v[18:33], v[166:169], v[66:69], v[18:33]
	s_cselect_b64 s[0:1], -1, 0
	s_or_b64 s[4:5], s[4:5], s[0:1]
	s_and_b64 vcc, exec, s[4:5]
	v_mfma_f32_32x32x16_bf16 v[34:49], v[170:173], v[66:69], v[34:49]
	v_mfma_f32_32x32x16_bf16 v[50:65], v[154:157], v[66:69], v[50:65]
	s_cbranch_vccz .LBB0_327

; __device__ __forceinline__ void attn_task(const AttnP& P, LAS unsigned char* lds, int b, int hd, int qq, int c, float shift, int lane_in) {
;     ...
;         if (gi < 10 && (ph >= 2 || li >= 26)) {
;             attn_load_v(P, lds, hb, gi, c, R0, lane, vf);
; #pragma unroll
;             for (int kk = 0; kk < 4; ++kk) kf[kk] = gk[kk];
;             if (gi < 4) {
;                 if (gi == 0) { w0 = mT0[0]; w1 = mT0[1]; } else if (gi == 3) { w0 = mT3[0]; w1 = mT3[1]; } else { w0 = 0x0101010101010101ull; w1 = 0x0101010101010101ull; }
;             } else if (gi < 7) {
;                 const bool pos = c > ((c + 4 * (gi - 3)) & 15);
;                 w0 = pos ? mAp[0] : mAn[0]; w1 = pos ? mAp[1] : mAn[1];
;             } else {
;                 { int cg, Rg; run_desc(gi, h, c, R0, cg, Rg); w0 = (c > cg) ? mLp : mLn; }
;                 { int cg, Rg; run_desc(gi, 2 + h, c, R0, cg, Rg); w1 = (c > cg) ? mLp : mLn; }
;             }
.LBB0_258:
	s_and_b64 vcc, exec, s[0:1]
	s_cbranch_vccz .LBB0_324
	s_cmp_gt_i32 s14, 3
	s_cselect_b64 s[8:9], -1, 0
	s_lshl_b32 s21, s14, 2
	s_sub_i32 s24, s21, 28
	s_cmp_gt_u32 s14, 6
	s_cselect_b64 s[0:1], -1, 0
	s_add_i32 s4, s21, s70
	s_waitcnt lgkmcnt(3)
	v_cndmask_b32_e64 v66, 0, 1, s[0:1]
	s_and_b32 s22, s4, 15
	s_mov_b64 s[10:11], -1
	s_and_b64 vcc, exec, s[8:9]
	v_cmp_ne_u32_e64 s[4:5], 1, v66
	s_cbranch_vccz .LBB0_263
	s_and_b64 vcc, exec, s[4:5]
	v_mov_b32_e32 v67, s22
	v_mov_b32_e32 v66, v234
	s_cbranch_vccnz .LBB0_262
	v_add_u32_e32 v66, s24, v228
	v_mul_lo_u32 v67, v66, 11
	v_lshrrev_b32_e32 v67, 5, v67
	v_add3_u32 v66, v66, s65, v67
	v_and_b32_e32 v67, 15, v66
	v_mov_b32_e32 v66, s15

; __device__ __forceinline__ int next_tile(int tt, int R0) { while (tt < 26 && !tile_valid(tt, R0)) ++tt; return tt; }
; __device__ __forceinline__ void attn_task(const AttnP& P, LAS unsigned char* lds, int b, int hd, int qq, int c, float shift, int lane_in) {
;     ...
;         if (gi < 10 && (ph >= 2 || li >= 26)) {
;             attn_load_v(P, lds, hb, gi, c, R0, lane, vf);
; #pragma unroll
;             for (int kk = 0; kk < 4; ++kk) kf[kk] = gk[kk];
;             if (gi < 4) {
;                 if (gi == 0) { w0 = mT0[0]; w1 = mT0[1]; } else if (gi == 3) { w0 = mT3[0]; w1 = mT3[1]; } else { w0 = 0x0101010101010101ull; w1 = 0x0101010101010101ull; }
;             } else if (gi < 7) {
;                 const bool pos = c > ((c + 4 * (gi - 3)) & 15);
;                 w0 = pos ? mAp[0] : mAn[0]; w1 = pos ? mAp[1] : mAn[1];
;             } else {
;                 { int cg, Rg; run_desc(gi, h, c, R0, cg, Rg); w0 = (c > cg) ? mLp : mLn; }
;                 { int cg, Rg; run_desc(gi, 2 + h, c, R0, cg, Rg); w1 = (c > cg) ? mLp : mLn; }
;             }
;             gi = next_tile(gi + 1, R0);
;             if (gi < 10) attn_load_k(P, lds, hb, gi, c, R0, lane, gk);
.LBB0_283:
	s_add_i32 s0, s21, 4
	s_max_i32 s0, s0, s17
	s_not_b32 s1, s21
	s_add_i32 s0, s0, s1
	s_max_i32 s1, s14, 3
	s_lshr_b32 s0, s0, 2
	s_sub_i32 s1, s1, s14
	s_min_u32 s0, s0, s1
	s_add_i32 s0, s14, s0
	s_add_i32 s14, s0, 1
	s_waitcnt vmcnt(4)
	v_mov_b64_e32 v[184:185], v[108:109]
	v_mov_b64_e32 v[182:183], v[106:107]
	v_mov_b64_e32 v[176:177], v[132:133]
	v_mov_b64_e32 v[174:175], v[130:131]
	v_mov_b64_e32 v[180:181], v[128:129]
	v_mov_b64_e32 v[178:179], v[126:127]
	v_mov_b64_e32 v[68:69], v[112:113]
	v_mov_b64_e32 v[66:67], v[110:111]
	s_cmp_gt_i32 s0, 8
	s_cbranch_scc1 .Lattn_nopf_2
	s_lshl_b32 s4, s14, 2
	s_cmp_gt_i32 s0, 2
	s_mov_b64 s[0:1], -1
	s_cbranch_scc0 .LBB0_290
	s_cmp_gt_u32 s14, 6
	s_cbranch_scc0 .LBB0_287
	v_add_u32_e32 v70, s4, v17
	v_mul_lo_u32 v71, v70, 11
	v_lshrrev_b32_e32 v71, 5, v71
	v_add3_u32 v70, v70, s65, v71
	v_and_b32_e32 v70, 15, v70
	s_mov_b64 s[0:1], 0
.LBB0_287:
	s_andn2_b64 vcc, exec, s[0:1]
	v_mov_b32_e32 v71, s15
	s_cbranch_vccnz .LBB0_289
	s_add_i32 s0, s4, s70
	s_and_b32 s0, s0, 15
	v_mov_b32_e32 v70, s0
	v_mov_b32_e32 v71, v231

; __device__ __forceinline__ void run_desc(int tt, int g, int c, int R0, int& cg, int& Rg) {
;     if (tt < 4) { cg = c; Rg = R0 - 16 + 4 * tt + g; }
;     else if (tt < 7) { cg = (c + 4 * (tt - 3)) & 15; Rg = R0 - 4 + g; }
;     else if (tt < 10) { const int o = 4 * (tt - 7) + g; const int o3 = (o * 11) >> 5; cg = (c + 1 + o3 * 4 + (o - 3 * o3)) & 15; Rg = R0 - 1; }
;     else { cg = tt - 10; Rg = R0 + g; }
; }
.LBB0_290:
	s_andn2_b64 vcc, exec, s[0:1]
	s_cbranch_vccnz .LBB0_292
	v_add_u32_e32 v71, s4, v232
	v_mov_b32_e32 v70, s64

; #define PG8_BAR __builtin_amdgcn_s_barrier()
; template <class Epi, class Sched>
; __device__ __forceinline__ void gemm_phase(LAS unsigned char* lds, const Gemm g, const Sched& S, const Epi& E) {
;     ...
;     const int tid = tid_, wid = __builtin_amdgcn_readfirstlane(tid >> 6), lane = tid & 63, wr = wid >> 2, wc = wid & 3, fr = lane & 15, fq = lane >> 4;
;     const int K = g.K, nt = K / BK;
;     unsigned voffA[2], voffB[2];
; #pragma unroll
;     for (int i = 0; i < 2; ++i) { int R, C; stage_rc(tid * 16 + i * 8192, R, C);
;         const int Ra = 128 * (R >> 6) + (R & 63);
;         const int Rb = Epi::HEADPERM ? (64 * (R >> 5) + perm32(R & 31)) : ((R & ~31) + perm32(R & 31));
;         voffA[i] = (unsigned)(Ra * g.lda + C) * 2u; voffB[i] = (unsigned)(Rb * K + C) * 2u; }
;     ...
;     const char* cA = (const char*)g.A + (size_t)cur.pm * tstep; const char* cB = (const char*)g.Bt + (size_t)cur.pn * tstep;
;     PG8_STAGE(PG8_SB(0, 0), cB, voffB); PG8_STAGE(PG8_SB(0, 1), cB + hstepB, voffB); PG8_STAGE(PG8_SA(0, 0), cA, voffA); PG8_STAGE(PG8_SA(0, 1), cA + hstepA, voffA);
;     if (wr == 1) PG8_BAR;
.LBB0_699:
	v_readlane_b32 s0, v243, 4
	v_mov_b32_e32 v2, v0
	v_readlane_b32 s1, v243, 5
	s_andn2_b64 vcc, exec, s[0:1]
	v_readfirstlane_b32 s1, v2
	s_cbranch_vccnz .LBB0_719
	s_mov_b32 s100, -1
	v_bfe_i32 v5, v2, 27, 1
	v_lshlrev_b32_e32 v3, 4, v2
	v_lshrrev_b32_e32 v5, 22, v5
	v_add_u32_e32 v5, v3, v5
	v_and_b32_e32 v5, 0xfffffc00, v5
	v_sub_u32_e32 v5, v3, v5
	v_ashrrev_i32_e32 v4, 31, v2
	v_lshrrev_b32_e32 v6, 4, v5
	v_lshrrev_b32_e32 v4, 26, v4
	v_bitop3_b32 v5, v6, v5, 32 bitop3:0x6c
	v_add_u32_e32 v4, v2, v4
	v_ashrrev_i32_e32 v7, 31, v5
	v_ashrrev_i32_e32 v4, 6, v4
	v_lshrrev_b32_e32 v7, 26, v7
	v_lshlrev_b32_e32 v6, 3, v4
	v_add_u32_e32 v7, v5, v7
	v_and_b32_e32 v6, -16, v6
	v_ashrrev_i32_e32 v8, 6, v7
	v_and_b32_e32 v7, 0xc0, v7
	v_add_u32_e32 v6, v8, v6
	v_sub_u32_e32 v5, v5, v7
	v_lshlrev_b32_e32 v4, 5, v4
	v_ashrrev_i16_sdwa v5, v164, sext(v5) dst_sel:DWORD dst_unused:UNUSED_PAD src0_sel:DWORD src1_sel:BYTE_0
	v_lshlrev_b32_e32 v7, 1, v6
	v_and_b32_e32 v9, 63, v6
	s_mov_b32 s4, 0x1fff80
	v_lshrrev_b32_e32 v10, 2, v6
	v_and_b32_e32 v8, 3, v8
	s_mov_b32 s5, 0x1fffe0
	v_and_b32_e32 v4, 32, v4
	v_bfe_i32 v5, v5, 0, 16
	v_and_or_b32 v9, v7, s4, v9
	v_and_b32_e32 v7, 24, v7
	v_and_b32_e32 v10, 4, v10
	v_and_or_b32 v6, v6, s5, v8
	v_or3_b32 v6, v6, v10, v7
	v_add_lshl_u32 v4, v4, v5, 1
	v_add_u32_e32 v3, 0x2000, v3
	v_lshl_add_u32 v165, v9, 11, v4
	v_lshl_add_u32 v166, v6, 11, v4
	v_ashrrev_i32_e32 v4, 31, v3
	v_lshrrev_b32_e32 v4, 22, v4
	v_add_u32_e32 v4, v3, v4
	v_ashrrev_i32_e32 v4, 10, v4
	v_mul_i32_i24_e32 v5, 0x400, v4
	v_sub_u32_e32 v3, v3, v5
	v_lshrrev_b32_e32 v5, 4, v3
	v_bitop3_b32 v3, v5, v3, 32 bitop3:0x6c
	v_ashrrev_i32_e32 v6, 31, v3
	v_lshrrev_b32_e32 v6, 26, v6
	v_lshlrev_b32_e32 v5, 3, v4
	v_add_u32_e32 v6, v3, v6
	v_and_b32_e32 v5, -16, v5
	v_ashrrev_i32_e32 v7, 6, v6
	v_and_b32_e32 v6, 0xc0, v6
	s_ashr_i32 s0, s1, 6
	v_add_u32_e32 v5, v7, v5
	v_sub_u32_e32 v3, v3, v6
	v_and_b32_e32 v7, 3, v7
	v_lshlrev_b32_e32 v4, 5, v4
	v_ashrrev_i16_sdwa v3, v164, sext(v3) dst_sel:DWORD dst_unused:UNUSED_PAD src0_sel:DWORD src1_sel:BYTE_0
	v_lshlrev_b32_e32 v6, 1, v5
	v_and_b32_e32 v8, 63, v5
	v_lshrrev_b32_e32 v9, 2, v5
	v_and_or_b32 v5, v5, s5, v7
	s_lshl_b32 s5, s0, 10
	v_and_b32_e32 v4, 32, v4
	v_bfe_i32 v3, v3, 0, 16
	v_and_or_b32 v8, v6, s4, v8
	v_and_b32_e32 v6, 24, v6
	v_and_b32_e32 v9, 4, v9
	v_readlane_b32 s6, v243, 28
	s_add_i32 s35, s5, 0
	v_or3_b32 v5, v5, v9, v6
	v_add_lshl_u32 v3, v4, v3, 1
	s_add_i32 s10, s34, s6
	s_add_i32 s64, s35, 0x10000
	s_mov_b32 s5, m0
	s_mov_b32 m0, s64
	s_nop 0
	global_load_lds_dwordx4 v166, s[70:71]
	s_mov_b32 m0, s5
	v_lshl_add_u32 v168, v5, 11, v3
	s_ashr_i32 s11, s10, 31
	s_add_i32 s65, s35, 0x12000
	s_mov_b32 s5, m0
	s_mov_b32 m0, s65
	s_nop 0
	global_load_lds_dwordx4 v168, s[70:71]
	s_mov_b32 m0, s5
	v_readlane_b32 s8, v243, 24
	s_ashr_i32 s4, s1, 8
	s_lshl_b64 s[6:7], s[10:11], 19
	s_add_i32 s38, s35, 0x14000
	v_readlane_b32 s9, v243, 25
	s_mov_b32 s5, m0
	s_mov_b32 m0, s38
	s_nop 0
	global_load_lds_dwordx4 v166, s[8:9]
	s_mov_b32 m0, s5
	s_add_i32 s39, s35, 0x16000
	s_mov_b32 s5, m0
	s_mov_b32 m0, s39
	s_nop 0
	global_load_lds_dwordx4 v168, s[8:9]
	s_mov_b32 m0, s5
	s_add_u32 s6, s42, s6
	s_addc_u32 s7, s43, s7
	s_mov_b32 s5, m0
	s_mov_b32 m0, s35
	s_nop 0
	global_load_lds_dwordx4 v165, s[6:7]
	s_mov_b32 m0, s5
	s_add_i32 s48, s35, 0x2000
	s_add_i32 s49, s35, 0x4000
	v_lshl_add_u32 v167, v8, 11, v3
	s_mov_b32 s5, m0
	s_mov_b32 m0, s48
	s_nop 0
	global_load_lds_dwordx4 v167, s[6:7]
	s_mov_b32 m0, s5
	s_add_u32 s8, s6, 0x20000
	s_addc_u32 s9, s7, 0
	s_mov_b32 s5, m0
	s_mov_b32 m0, s49
	s_nop 0
	global_load_lds_dwordx4 v165, s[8:9]
	s_mov_b32 m0, s5
	s_add_i32 s25, s35, 0x6000
	s_mov_b32 s5, m0
	s_mov_b32 m0, s25
	s_nop 0
	global_load_lds_dwordx4 v167, s[8:9]
	s_mov_b32 m0, s5
	s_cmp_eq_u32 s4, 1
	s_cselect_b64 s[96:97], -1, 0
	s_cmp_lg_u32 s4, 1
	s_cbranch_scc1 .LBB0_702
	s_barrier

; __device__ __forceinline__ unsigned pk2(float lo, float hi) { f32x2 v = {lo, hi}; bf16x2_t b = __builtin_convertvector(v, bf16x2_t); return __builtin_bit_cast(unsigned, b); }
;     __device__ __forceinline__ void operator()(const f32x4 (&acc)[2][2][4][2], const Unit& u, int wr, int wc, int fr, int fq) const {
; #pragma unroll
;         for (int ai = 0; ai < 2; ++ai)
; #pragma unroll
;             for (int m = 0; m < 4; ++m) {
;                 const size_t row = (size_t)u.pm * 256 + 128 * wr + 64 * ai + 16 * m + fr;
;                 const f32x4* sp = (const f32x4*)(ssq + row * 16);
;                 const f32x4 t = (sp[0] + sp[1]) + (sp[2] + sp[3]);
;                 const float r = __builtin_amdgcn_rsqf(((t[0] + t[1]) + (t[2] + t[3])) * (1.0f / DM) + EPS);
;                 const size_t off = (((size_t)u.pm * 64 + 4 * u.pn + (wc >> 1)) * 256 + (128 * wr + 64 * ai + 16 * m + fr)) * 64 + 32 * (wc & 1) + 8 * fq;
; #pragma unroll
;                 for (int bj = 0; bj < 2; ++bj) {
;                     f32x4 v0 = acc[ai][bj][m][0] * r, v1 = acc[ai][bj][m][1] * r;
; #pragma unroll
;                     for (int j = 0; j < 4; ++j) { v0[j] = fmaxf(v0[j], 0.f); v1[j] = fmaxf(v1[j], 0.f); }
;                     v0 = v0 * v0; v1 = v1 * v1;
;                     u32x4 w; w.x = pk2(v0[0], v0[1]); w.y = pk2(v0[2], v0[3]); w.z = pk2(v1[0], v1[1]); w.w = pk2(v1[2], v1[3]);
;                     *(u32x4*)(H + off + (size_t)bj * (2 * 256 * 64)) = w;
;                 }
.LBB0_715:
	s_ashr_i32 s11, s10, 31
	s_lshl_b32 s1, s29, 2
	s_lshl_b64 s[6:7], s[10:11], 6
	s_ashr_i32 s5, s1, 31
	s_add_u32 s6, s6, s1
	s_addc_u32 s7, s7, s5
	s_lshl_b64 s[10:11], s[10:11], 14
	v_lshl_add_u64 v[162:163], v[160:161], 0, s[10:11]
	s_cmp_eq_u32 s10, s100
	s_cbranch_scc1 .Lp4_rstd_cached
	s_mov_b32 s100, s10
	v_and_b32_e32 v236, 0x30, v0
	v_mov_b32_e32 v237, 0
	s_mov_b64 s[14:15], 0x1000
	v_lshl_add_u64 v[162:163], v[162:163], 0, v[236:237]
	v_lshl_add_u64 v[238:239], v[162:163], 0, s[14:15]
	global_load_dwordx4 v[172:175], v[162:163], off
	global_load_dwordx4 v[176:179], v[162:163], off offset:1024
	global_load_dwordx4 v[180:183], v[162:163], off offset:2048
	global_load_dwordx4 v[184:187], v[162:163], off offset:3072
	global_load_dwordx4 v[188:191], v[238:239], off
	global_load_dwordx4 v[192:195], v[238:239], off offset:1024
	global_load_dwordx4 v[196:199], v[238:239], off offset:2048
	global_load_dwordx4 v[200:203], v[238:239], off offset:3072
	s_waitcnt vmcnt(0)
	v_add_f32_e32 v172, v172, v173
	v_add_f32_e32 v176, v176, v177
	v_add_f32_e32 v180, v180, v181
	v_add_f32_e32 v184, v184, v185
	v_add_f32_e32 v188, v188, v189
	v_add_f32_e32 v192, v192, v193
	v_add_f32_e32 v196, v196, v197
	v_add_f32_e32 v200, v200, v201
	v_add_f32_e32 v174, v174, v175
	v_add_f32_e32 v178, v178, v179
	v_add_f32_e32 v182, v182, v183
	v_add_f32_e32 v186, v186, v187
	v_add_f32_e32 v190, v190, v191
	v_add_f32_e32 v194, v194, v195
	v_add_f32_e32 v198, v198, v199
	v_add_f32_e32 v202, v202, v203
	v_add_f32_e32 v172, v172, v174
	v_add_f32_e32 v176, v176, v178
	v_add_f32_e32 v180, v180, v182
	v_add_f32_e32 v184, v184, v186
	v_add_f32_e32 v188, v188, v190
	v_add_f32_e32 v192, v192, v194
	v_add_f32_e32 v196, v196, v198
	v_add_f32_e32 v200, v200, v202
	v_mov_b32_e32 v173, v172
	v_mov_b32_e32 v177, v176
	v_mov_b32_e32 v181, v180
	v_mov_b32_e32 v185, v184
	v_mov_b32_e32 v189, v188
	v_mov_b32_e32 v193, v192
	v_mov_b32_e32 v197, v196
	v_mov_b32_e32 v201, v200
	v_permlane16_swap_b32_e32 v172, v173
	v_permlane16_swap_b32_e32 v176, v177
	v_permlane16_swap_b32_e32 v180, v181
	v_permlane16_swap_b32_e32 v184, v185
	v_permlane16_swap_b32_e32 v188, v189
	v_permlane16_swap_b32_e32 v192, v193
	v_permlane16_swap_b32_e32 v196, v197
	v_permlane16_swap_b32_e32 v200, v201
	v_add_f32_e32 v172, v172, v173
	v_add_f32_e32 v176, v176, v177
	v_add_f32_e32 v180, v180, v181
	v_add_f32_e32 v184, v184, v185
	v_add_f32_e32 v188, v188, v189
	v_add_f32_e32 v192, v192, v193
	v_add_f32_e32 v196, v196, v197
	v_add_f32_e32 v200, v200, v201
	v_mov_b32_e32 v173, v172
	v_mov_b32_e32 v177, v176
	v_mov_b32_e32 v181, v180
	v_mov_b32_e32 v185, v184
	v_mov_b32_e32 v189, v188
	v_mov_b32_e32 v193, v192
	v_mov_b32_e32 v197, v196
	v_mov_b32_e32 v201, v200
	v_permlane32_swap_b32_e32 v172, v173
	v_permlane32_swap_b32_e32 v176, v177
	v_permlane32_swap_b32_e32 v180, v181
	v_permlane32_swap_b32_e32 v184, v185
	v_permlane32_swap_b32_e32 v188, v189
	v_permlane32_swap_b32_e32 v192, v193
	v_permlane32_swap_b32_e32 v196, v197
	v_permlane32_swap_b32_e32 v200, v201
	v_add_f32_e32 v172, v172, v173
	v_add_f32_e32 v176, v176, v177
	v_add_f32_e32 v180, v180, v181
	v_add_f32_e32 v184, v184, v185
	v_add_f32_e32 v188, v188, v189
	v_add_f32_e32 v192, v192, v193
	v_add_f32_e32 v196, v196, v197
	v_add_f32_e32 v200, v200, v201
	v_fmamk_f32 v172, v172, 0x3a800000, v1
	v_fmamk_f32 v176, v176, 0x3a800000, v1
	v_fmamk_f32 v180, v180, 0x3a800000, v1
	v_fmamk_f32 v184, v184, 0x3a800000, v1
	v_fmamk_f32 v188, v188, 0x3a800000, v1
	v_fmamk_f32 v192, v192, 0x3a800000, v1
	v_fmamk_f32 v196, v196, 0x3a800000, v1
	v_fmamk_f32 v200, v200, 0x3a800000, v1
	v_rsq_f32_e32 v244, v172
	v_rsq_f32_e32 v245, v176
	v_rsq_f32_e32 v246, v180
	v_rsq_f32_e32 v247, v184
	v_rsq_f32_e32 v248, v188
	v_rsq_f32_e32 v249, v192
	v_rsq_f32_e32 v250, v196
	v_rsq_f32_e32 v251, v200
.Lp4_rstd_cached:
	s_or_b64 s[6:7], s[6:7], s[86:87]
	s_lshl_b64 s[6:7], s[6:7], 15
	s_add_u32 s10, s46, s6
	s_addc_u32 s11, s47, s7
	s_mov_b64 s[14:15], 0x10000
	v_pk_mul_f32 v[114:115], v[114:115], v[244:245] op_sel_hi:[1,0]
	v_pk_mul_f32 v[116:117], v[116:117], v[244:245] op_sel_hi:[1,0]
	v_pk_mul_f32 v[118:119], v[118:119], v[244:245] op_sel_hi:[1,0]
	v_pk_mul_f32 v[120:121], v[120:121], v[244:245] op_sel_hi:[1,0]
	v_pk_mul_f32 v[122:123], v[122:123], v[244:245] op_sel_hi:[1,0]
	v_pk_mul_f32 v[124:125], v[124:125], v[244:245] op_sel_hi:[1,0]
	v_pk_mul_f32 v[126:127], v[126:127], v[244:245] op_sel_hi:[1,0]
	v_pk_mul_f32 v[128:129], v[128:129], v[244:245] op_sel_hi:[1,0]
	v_lshl_add_u64 v[204:205], s[10:11], 0, v[144:145]
	v_max_f32_e32 v114, 0, v114
	v_max_f32_e32 v115, 0, v115
	v_max_f32_e32 v116, 0, v116
	v_max_f32_e32 v117, 0, v117
	v_max_f32_e32 v118, 0, v118
	v_max_f32_e32 v119, 0, v119
	v_max_f32_e32 v120, 0, v120
	v_max_f32_e32 v121, 0, v121
	v_max_f32_e32 v122, 0, v122
	v_max_f32_e32 v123, 0, v123
	v_max_f32_e32 v124, 0, v124
	v_max_f32_e32 v125, 0, v125
	v_max_f32_e32 v126, 0, v126
	v_max_f32_e32 v127, 0, v127
	v_max_f32_e32 v128, 0, v128
	v_max_f32_e32 v129, 0, v129
	v_lshl_add_u64 v[204:205], v[204:205], 0, s[62:63]
	v_pk_mul_f32 v[114:115], v[114:115], v[114:115]
	v_pk_mul_f32 v[116:117], v[116:117], v[116:117]
	v_pk_mul_f32 v[118:119], v[118:119], v[118:119]
	v_pk_mul_f32 v[120:121], v[120:121], v[120:121]
	v_pk_mul_f32 v[122:123], v[122:123], v[122:123]
	v_pk_mul_f32 v[124:125], v[124:125], v[124:125]
	v_pk_mul_f32 v[126:127], v[126:127], v[126:127]
	v_pk_mul_f32 v[128:129], v[128:129], v[128:129]
	v_lshl_add_u64 v[204:205], v[204:205], 0, v[134:135]
	v_cvt_pk_bf16_f32 v126, v126, v127
	v_cvt_pk_bf16_f32 v127, v128, v129
	v_cvt_pk_bf16_f32 v128, v122, v123
; __device__ __forceinline__ unsigned pk2(float lo, float hi) { f32x2 v = {lo, hi}; bf16x2_t b = __builtin_convertvector(v, bf16x2_t); return __builtin_bit_cast(unsigned, b); }
;     __device__ __forceinline__ void operator()(const f32x4 (&acc)[2][2][4][2], const Unit& u, int wr, int wc, int fr, int fq) const {
; #pragma unroll
;         for (int ai = 0; ai < 2; ++ai)
; #pragma unroll
;             for (int m = 0; m < 4; ++m) {
;                 const size_t row = (size_t)u.pm * 256 + 128 * wr + 64 * ai + 16 * m + fr;
;                 const f32x4* sp = (const f32x4*)(ssq + row * 16);
;                 const f32x4 t = (sp[0] + sp[1]) + (sp[2] + sp[3]);
;                 const float r = __builtin_amdgcn_rsqf(((t[0] + t[1]) + (t[2] + t[3])) * (1.0f / DM) + EPS);
;                 const size_t off = (((size_t)u.pm * 64 + 4 * u.pn + (wc >> 1)) * 256 + (128 * wr + 64 * ai + 16 * m + fr)) * 64 + 32 * (wc & 1) + 8 * fq;
; #pragma unroll
;                 for (int bj = 0; bj < 2; ++bj) {
;                     f32x4 v0 = acc[ai][bj][m][0] * r, v1 = acc[ai][bj][m][1] * r;
; #pragma unroll
;                     for (int j = 0; j < 4; ++j) { v0[j] = fmaxf(v0[j], 0.f); v1[j] = fmaxf(v1[j], 0.f); }
;                     v0 = v0 * v0; v1 = v1 * v1;
;                     u32x4 w; w.x = pk2(v0[0], v0[1]); w.y = pk2(v0[2], v0[3]); w.z = pk2(v1[0], v1[1]); w.w = pk2(v1[2], v1[3]);
;                     *(u32x4*)(H + off + (size_t)bj * (2 * 256 * 64)) = w;
;                 }
	v_cvt_pk_bf16_f32 v129, v124, v125
	v_lshl_add_u64 v[206:207], v[204:205], 0, s[14:15]
	global_store_dwordx4 v[204:205], v[126:129], off
	v_cvt_pk_bf16_f32 v118, v118, v119
	v_cvt_pk_bf16_f32 v119, v120, v121
	v_cvt_pk_bf16_f32 v120, v114, v115
	v_cvt_pk_bf16_f32 v121, v116, v117
	global_store_dwordx4 v[206:207], v[118:121], off
	v_pk_mul_f32 v[98:99], v[98:99], v[244:245] op_sel:[0,1]
	v_pk_mul_f32 v[100:101], v[100:101], v[244:245] op_sel:[0,1]
	v_pk_mul_f32 v[102:103], v[102:103], v[244:245] op_sel:[0,1]
	v_pk_mul_f32 v[104:105], v[104:105], v[244:245] op_sel:[0,1]
	v_pk_mul_f32 v[106:107], v[106:107], v[244:245] op_sel:[0,1]
	v_pk_mul_f32 v[108:109], v[108:109], v[244:245] op_sel:[0,1]
	v_pk_mul_f32 v[110:111], v[110:111], v[244:245] op_sel:[0,1]
	v_pk_mul_f32 v[112:113], v[112:113], v[244:245] op_sel:[0,1]
	v_lshl_add_u64 v[204:205], s[10:11], 0, v[146:147]
	v_max_f32_e32 v98, 0, v98
	v_max_f32_e32 v99, 0, v99
	v_max_f32_e32 v100, 0, v100
	v_max_f32_e32 v101, 0, v101
	v_max_f32_e32 v102, 0, v102
	v_max_f32_e32 v103, 0, v103
	v_max_f32_e32 v104, 0, v104
	v_max_f32_e32 v105, 0, v105
	v_max_f32_e32 v106, 0, v106
	v_max_f32_e32 v107, 0, v107
	v_max_f32_e32 v108, 0, v108
	v_max_f32_e32 v109, 0, v109
	v_max_f32_e32 v110, 0, v110
	v_max_f32_e32 v111, 0, v111
	v_max_f32_e32 v112, 0, v112
	v_max_f32_e32 v113, 0, v113
	v_lshl_add_u64 v[204:205], v[204:205], 0, s[62:63]
	v_pk_mul_f32 v[98:99], v[98:99], v[98:99]
	v_pk_mul_f32 v[100:101], v[100:101], v[100:101]
	v_pk_mul_f32 v[102:103], v[102:103], v[102:103]
	v_pk_mul_f32 v[104:105], v[104:105], v[104:105]
	v_pk_mul_f32 v[106:107], v[106:107], v[106:107]
	v_pk_mul_f32 v[108:109], v[108:109], v[108:109]
	v_pk_mul_f32 v[110:111], v[110:111], v[110:111]
	v_pk_mul_f32 v[112:113], v[112:113], v[112:113]
	v_lshl_add_u64 v[204:205], v[204:205], 0, v[134:135]
	v_cvt_pk_bf16_f32 v110, v110, v111
	v_cvt_pk_bf16_f32 v111, v112, v113
	v_cvt_pk_bf16_f32 v112, v106, v107
	v_cvt_pk_bf16_f32 v113, v108, v109
	v_lshl_add_u64 v[206:207], v[204:205], 0, s[14:15]
	global_store_dwordx4 v[204:205], v[110:113], off
	v_cvt_pk_bf16_f32 v102, v102, v103
	v_cvt_pk_bf16_f32 v103, v104, v105
	v_cvt_pk_bf16_f32 v104, v98, v99
	v_cvt_pk_bf16_f32 v105, v100, v101
	global_store_dwordx4 v[206:207], v[102:105], off
	v_pk_mul_f32 v[82:83], v[82:83], v[246:247] op_sel_hi:[1,0]
	v_pk_mul_f32 v[84:85], v[84:85], v[246:247] op_sel_hi:[1,0]
	v_pk_mul_f32 v[86:87], v[86:87], v[246:247] op_sel_hi:[1,0]
	v_pk_mul_f32 v[88:89], v[88:89], v[246:247] op_sel_hi:[1,0]
	v_pk_mul_f32 v[90:91], v[90:91], v[246:247] op_sel_hi:[1,0]
	v_pk_mul_f32 v[92:93], v[92:93], v[246:247] op_sel_hi:[1,0]
	v_pk_mul_f32 v[94:95], v[94:95], v[246:247] op_sel_hi:[1,0]
	v_pk_mul_f32 v[96:97], v[96:97], v[246:247] op_sel_hi:[1,0]
	v_lshl_add_u64 v[204:205], s[10:11], 0, v[148:149]
	v_max_f32_e32 v82, 0, v82
	v_max_f32_e32 v83, 0, v83
	v_max_f32_e32 v84, 0, v84
	v_max_f32_e32 v85, 0, v85
	v_max_f32_e32 v86, 0, v86
	v_max_f32_e32 v87, 0, v87
	v_max_f32_e32 v88, 0, v88
	v_max_f32_e32 v89, 0, v89
	v_max_f32_e32 v90, 0, v90
	v_max_f32_e32 v91, 0, v91
	v_max_f32_e32 v92, 0, v92
	v_max_f32_e32 v93, 0, v93
	v_max_f32_e32 v94, 0, v94
	v_max_f32_e32 v95, 0, v95
	v_max_f32_e32 v96, 0, v96
	v_max_f32_e32 v97, 0, v97
	v_lshl_add_u64 v[204:205], v[204:205], 0, s[62:63]
	v_pk_mul_f32 v[82:83], v[82:83], v[82:83]
	v_pk_mul_f32 v[84:85], v[84:85], v[84:85]
	v_pk_mul_f32 v[86:87], v[86:87], v[86:87]
	v_pk_mul_f32 v[88:89], v[88:89], v[88:89]
	v_pk_mul_f32 v[90:91], v[90:91], v[90:91]
	v_pk_mul_f32 v[92:93], v[92:93], v[92:93]
	v_pk_mul_f32 v[94:95], v[94:95], v[94:95]
	v_pk_mul_f32 v[96:97], v[96:97], v[96:97]
	v_lshl_add_u64 v[204:205], v[204:205], 0, v[134:135]
	v_cvt_pk_bf16_f32 v94, v94, v95
	v_cvt_pk_bf16_f32 v95, v96, v97
	v_cvt_pk_bf16_f32 v96, v90, v91
	v_cvt_pk_bf16_f32 v97, v92, v93
	v_lshl_add_u64 v[206:207], v[204:205], 0, s[14:15]
	global_store_dwordx4 v[204:205], v[94:97], off
	v_cvt_pk_bf16_f32 v86, v86, v87
	v_cvt_pk_bf16_f32 v87, v88, v89
	v_cvt_pk_bf16_f32 v88, v82, v83
	v_cvt_pk_bf16_f32 v89, v84, v85
	global_store_dwordx4 v[206:207], v[86:89], off
	v_pk_mul_f32 v[66:67], v[66:67], v[246:247] op_sel:[0,1]
	v_pk_mul_f32 v[68:69], v[68:69], v[246:247] op_sel:[0,1]
	v_pk_mul_f32 v[70:71], v[70:71], v[246:247] op_sel:[0,1]
	v_pk_mul_f32 v[72:73], v[72:73], v[246:247] op_sel:[0,1]
	v_pk_mul_f32 v[74:75], v[74:75], v[246:247] op_sel:[0,1]
	v_pk_mul_f32 v[76:77], v[76:77], v[246:247] op_sel:[0,1]
	v_pk_mul_f32 v[78:79], v[78:79], v[246:247] op_sel:[0,1]
	v_pk_mul_f32 v[80:81], v[80:81], v[246:247] op_sel:[0,1]
	v_lshl_add_u64 v[204:205], s[10:11], 0, v[150:151]
	v_max_f32_e32 v66, 0, v66
	v_max_f32_e32 v67, 0, v67
	v_max_f32_e32 v68, 0, v68
	v_max_f32_e32 v69, 0, v69
	v_max_f32_e32 v70, 0, v70
	v_max_f32_e32 v71, 0, v71
	v_max_f32_e32 v72, 0, v72
	v_max_f32_e32 v73, 0, v73
	v_max_f32_e32 v74, 0, v74
	v_max_f32_e32 v75, 0, v75
	v_max_f32_e32 v76, 0, v76
	v_max_f32_e32 v77, 0, v77
	v_max_f32_e32 v78, 0, v78
	v_max_f32_e32 v79, 0, v79
	v_max_f32_e32 v80, 0, v80
	v_max_f32_e32 v81, 0, v81
	v_lshl_add_u64 v[204:205], v[204:205], 0, s[62:63]
	v_pk_mul_f32 v[66:67], v[66:67], v[66:67]
	v_pk_mul_f32 v[68:69], v[68:69], v[68:69]
	v_pk_mul_f32 v[70:71], v[70:71], v[70:71]
	v_pk_mul_f32 v[72:73], v[72:73], v[72:73]
	v_pk_mul_f32 v[74:75], v[74:75], v[74:75]
	v_pk_mul_f32 v[76:77], v[76:77], v[76:77]
	v_pk_mul_f32 v[78:79], v[78:79], v[78:79]
	v_pk_mul_f32 v[80:81], v[80:81], v[80:81]
	v_lshl_add_u64 v[204:205], v[204:205], 0, v[134:135]
	v_cvt_pk_bf16_f32 v78, v78, v79
	v_cvt_pk_bf16_f32 v79, v80, v81
	v_cvt_pk_bf16_f32 v80, v74, v75
	v_cvt_pk_bf16_f32 v81, v76, v77
; __device__ __forceinline__ unsigned pk2(float lo, float hi) { f32x2 v = {lo, hi}; bf16x2_t b = __builtin_convertvector(v, bf16x2_t); return __builtin_bit_cast(unsigned, b); }
;     __device__ __forceinline__ void operator()(const f32x4 (&acc)[2][2][4][2], const Unit& u, int wr, int wc, int fr, int fq) const {
; #pragma unroll
;         for (int ai = 0; ai < 2; ++ai)
; #pragma unroll
;             for (int m = 0; m < 4; ++m) {
;                 const size_t row = (size_t)u.pm * 256 + 128 * wr + 64 * ai + 16 * m + fr;
;                 const f32x4* sp = (const f32x4*)(ssq + row * 16);
;                 const f32x4 t = (sp[0] + sp[1]) + (sp[2] + sp[3]);
;                 const float r = __builtin_amdgcn_rsqf(((t[0] + t[1]) + (t[2] + t[3])) * (1.0f / DM) + EPS);
;                 const size_t off = (((size_t)u.pm * 64 + 4 * u.pn + (wc >> 1)) * 256 + (128 * wr + 64 * ai + 16 * m + fr)) * 64 + 32 * (wc & 1) + 8 * fq;
; #pragma unroll
;                 for (int bj = 0; bj < 2; ++bj) {
;                     f32x4 v0 = acc[ai][bj][m][0] * r, v1 = acc[ai][bj][m][1] * r;
; #pragma unroll
;                     for (int j = 0; j < 4; ++j) { v0[j] = fmaxf(v0[j], 0.f); v1[j] = fmaxf(v1[j], 0.f); }
;                     v0 = v0 * v0; v1 = v1 * v1;
;                     u32x4 w; w.x = pk2(v0[0], v0[1]); w.y = pk2(v0[2], v0[3]); w.z = pk2(v1[0], v1[1]); w.w = pk2(v1[2], v1[3]);
;                     *(u32x4*)(H + off + (size_t)bj * (2 * 256 * 64)) = w;
;                 }
	v_lshl_add_u64 v[206:207], v[204:205], 0, s[14:15]
	global_store_dwordx4 v[204:205], v[78:81], off
	v_cvt_pk_bf16_f32 v70, v70, v71
	v_cvt_pk_bf16_f32 v71, v72, v73
	v_cvt_pk_bf16_f32 v72, v66, v67
	v_cvt_pk_bf16_f32 v73, v68, v69
	global_store_dwordx4 v[206:207], v[70:73], off
	v_pk_mul_f32 v[50:51], v[50:51], v[248:249] op_sel_hi:[1,0]
	v_pk_mul_f32 v[52:53], v[52:53], v[248:249] op_sel_hi:[1,0]
	v_pk_mul_f32 v[54:55], v[54:55], v[248:249] op_sel_hi:[1,0]
	v_pk_mul_f32 v[56:57], v[56:57], v[248:249] op_sel_hi:[1,0]
	v_pk_mul_f32 v[58:59], v[58:59], v[248:249] op_sel_hi:[1,0]
	v_pk_mul_f32 v[60:61], v[60:61], v[248:249] op_sel_hi:[1,0]
	v_pk_mul_f32 v[62:63], v[62:63], v[248:249] op_sel_hi:[1,0]
	v_pk_mul_f32 v[64:65], v[64:65], v[248:249] op_sel_hi:[1,0]
	v_lshl_add_u64 v[204:205], s[10:11], 0, v[152:153]
	v_max_f32_e32 v50, 0, v50
	v_max_f32_e32 v51, 0, v51
	v_max_f32_e32 v52, 0, v52
	v_max_f32_e32 v53, 0, v53
	v_max_f32_e32 v54, 0, v54
	v_max_f32_e32 v55, 0, v55
	v_max_f32_e32 v56, 0, v56
	v_max_f32_e32 v57, 0, v57
	v_max_f32_e32 v58, 0, v58
	v_max_f32_e32 v59, 0, v59
	v_max_f32_e32 v60, 0, v60
	v_max_f32_e32 v61, 0, v61
	v_max_f32_e32 v62, 0, v62
	v_max_f32_e32 v63, 0, v63
	v_max_f32_e32 v64, 0, v64
	v_max_f32_e32 v65, 0, v65
	v_lshl_add_u64 v[204:205], v[204:205], 0, s[62:63]
	v_pk_mul_f32 v[50:51], v[50:51], v[50:51]
	v_pk_mul_f32 v[52:53], v[52:53], v[52:53]
	v_pk_mul_f32 v[54:55], v[54:55], v[54:55]
	v_pk_mul_f32 v[56:57], v[56:57], v[56:57]
	v_pk_mul_f32 v[58:59], v[58:59], v[58:59]
	v_pk_mul_f32 v[60:61], v[60:61], v[60:61]
	v_pk_mul_f32 v[62:63], v[62:63], v[62:63]
	v_pk_mul_f32 v[64:65], v[64:65], v[64:65]
	v_lshl_add_u64 v[204:205], v[204:205], 0, v[134:135]
	v_cvt_pk_bf16_f32 v62, v62, v63
	v_cvt_pk_bf16_f32 v63, v64, v65
	v_cvt_pk_bf16_f32 v64, v58, v59
	v_cvt_pk_bf16_f32 v65, v60, v61
	v_lshl_add_u64 v[206:207], v[204:205], 0, s[14:15]
	global_store_dwordx4 v[204:205], v[62:65], off
	v_cvt_pk_bf16_f32 v54, v54, v55
	v_cvt_pk_bf16_f32 v55, v56, v57
	v_cvt_pk_bf16_f32 v56, v50, v51
	v_cvt_pk_bf16_f32 v57, v52, v53
	global_store_dwordx4 v[206:207], v[54:57], off
	v_pk_mul_f32 v[34:35], v[34:35], v[248:249] op_sel:[0,1]
	v_pk_mul_f32 v[36:37], v[36:37], v[248:249] op_sel:[0,1]
	v_pk_mul_f32 v[38:39], v[38:39], v[248:249] op_sel:[0,1]
	v_pk_mul_f32 v[40:41], v[40:41], v[248:249] op_sel:[0,1]
	v_pk_mul_f32 v[42:43], v[42:43], v[248:249] op_sel:[0,1]
	v_pk_mul_f32 v[44:45], v[44:45], v[248:249] op_sel:[0,1]
	v_pk_mul_f32 v[46:47], v[46:47], v[248:249] op_sel:[0,1]
	v_pk_mul_f32 v[48:49], v[48:49], v[248:249] op_sel:[0,1]
	v_lshl_add_u64 v[204:205], s[10:11], 0, v[154:155]
	v_max_f32_e32 v34, 0, v34
	v_max_f32_e32 v35, 0, v35
	v_max_f32_e32 v36, 0, v36
	v_max_f32_e32 v37, 0, v37
	v_max_f32_e32 v38, 0, v38
	v_max_f32_e32 v39, 0, v39
	v_max_f32_e32 v40, 0, v40
	v_max_f32_e32 v41, 0, v41
	v_max_f32_e32 v42, 0, v42
	v_max_f32_e32 v43, 0, v43
	v_max_f32_e32 v44, 0, v44
	v_max_f32_e32 v45, 0, v45
	v_max_f32_e32 v46, 0, v46
	v_max_f32_e32 v47, 0, v47
	v_max_f32_e32 v48, 0, v48
	v_max_f32_e32 v49, 0, v49
	v_lshl_add_u64 v[204:205], v[204:205], 0, s[62:63]
	v_pk_mul_f32 v[34:35], v[34:35], v[34:35]
	v_pk_mul_f32 v[36:37], v[36:37], v[36:37]
	v_pk_mul_f32 v[38:39], v[38:39], v[38:39]
	v_pk_mul_f32 v[40:41], v[40:41], v[40:41]
	v_pk_mul_f32 v[42:43], v[42:43], v[42:43]
	v_pk_mul_f32 v[44:45], v[44:45], v[44:45]
	v_pk_mul_f32 v[46:47], v[46:47], v[46:47]
	v_pk_mul_f32 v[48:49], v[48:49], v[48:49]
	v_lshl_add_u64 v[204:205], v[204:205], 0, v[134:135]
	v_cvt_pk_bf16_f32 v46, v46, v47
	v_cvt_pk_bf16_f32 v47, v48, v49
	v_cvt_pk_bf16_f32 v48, v42, v43
	v_cvt_pk_bf16_f32 v49, v44, v45
	v_lshl_add_u64 v[206:207], v[204:205], 0, s[14:15]
	global_store_dwordx4 v[204:205], v[46:49], off
	v_cvt_pk_bf16_f32 v38, v38, v39
	v_cvt_pk_bf16_f32 v39, v40, v41
	v_cvt_pk_bf16_f32 v40, v34, v35
; __device__ __forceinline__ unsigned pk2(float lo, float hi) { f32x2 v = {lo, hi}; bf16x2_t b = __builtin_convertvector(v, bf16x2_t); return __builtin_bit_cast(unsigned, b); }
; #define PG8_BAR __builtin_amdgcn_s_barrier()
;     __device__ __forceinline__ void operator()(const f32x4 (&acc)[2][2][4][2], const Unit& u, int wr, int wc, int fr, int fq) const {
; #pragma unroll
;         for (int ai = 0; ai < 2; ++ai)
; #pragma unroll
;             for (int m = 0; m < 4; ++m) {
;                 const size_t row = (size_t)u.pm * 256 + 128 * wr + 64 * ai + 16 * m + fr;
;                 const f32x4* sp = (const f32x4*)(ssq + row * 16);
;                 const f32x4 t = (sp[0] + sp[1]) + (sp[2] + sp[3]);
;                 const float r = __builtin_amdgcn_rsqf(((t[0] + t[1]) + (t[2] + t[3])) * (1.0f / DM) + EPS);
;                 const size_t off = (((size_t)u.pm * 64 + 4 * u.pn + (wc >> 1)) * 256 + (128 * wr + 64 * ai + 16 * m + fr)) * 64 + 32 * (wc & 1) + 8 * fq;
; #pragma unroll
;                 for (int bj = 0; bj < 2; ++bj) {
;                     f32x4 v0 = acc[ai][bj][m][0] * r, v1 = acc[ai][bj][m][1] * r;
; #pragma unroll
;                     for (int j = 0; j < 4; ++j) { v0[j] = fmaxf(v0[j], 0.f); v1[j] = fmaxf(v1[j], 0.f); }
;                     v0 = v0 * v0; v1 = v1 * v1;
;                     u32x4 w; w.x = pk2(v0[0], v0[1]); w.y = pk2(v0[2], v0[3]); w.z = pk2(v1[0], v1[1]); w.w = pk2(v1[2], v1[3]);
;                     *(u32x4*)(H + off + (size_t)bj * (2 * 256 * 64)) = w;
;                 }
; template <class Epi, class Sched>
; __device__ __forceinline__ void gemm_phase(LAS unsigned char* lds, const Gemm g, const Sched& S, const Epi& E) {
;     ...
;         cur = nxt; cA = nA; cB = nB; ++ui;
;         if (wr == 1) PG8_BAR;
	v_cvt_pk_bf16_f32 v41, v36, v37
	global_store_dwordx4 v[206:207], v[38:41], off
	v_pk_mul_f32 v[18:19], v[18:19], v[250:251] op_sel_hi:[1,0]
	v_pk_mul_f32 v[20:21], v[20:21], v[250:251] op_sel_hi:[1,0]
	v_pk_mul_f32 v[22:23], v[22:23], v[250:251] op_sel_hi:[1,0]
	v_pk_mul_f32 v[24:25], v[24:25], v[250:251] op_sel_hi:[1,0]
	v_pk_mul_f32 v[26:27], v[26:27], v[250:251] op_sel_hi:[1,0]
	v_pk_mul_f32 v[28:29], v[28:29], v[250:251] op_sel_hi:[1,0]
	v_pk_mul_f32 v[30:31], v[30:31], v[250:251] op_sel_hi:[1,0]
	v_pk_mul_f32 v[32:33], v[32:33], v[250:251] op_sel_hi:[1,0]
	v_lshl_add_u64 v[204:205], s[10:11], 0, v[156:157]
	v_max_f32_e32 v18, 0, v18
	v_max_f32_e32 v19, 0, v19
	v_max_f32_e32 v20, 0, v20
	v_max_f32_e32 v21, 0, v21
	v_max_f32_e32 v22, 0, v22
	v_max_f32_e32 v23, 0, v23
	v_max_f32_e32 v24, 0, v24
	v_max_f32_e32 v25, 0, v25
	v_max_f32_e32 v26, 0, v26
	v_max_f32_e32 v27, 0, v27
	v_max_f32_e32 v28, 0, v28
	v_max_f32_e32 v29, 0, v29
	v_max_f32_e32 v30, 0, v30
	v_max_f32_e32 v31, 0, v31
	v_max_f32_e32 v32, 0, v32
	v_max_f32_e32 v33, 0, v33
	v_lshl_add_u64 v[204:205], v[204:205], 0, s[62:63]
	v_pk_mul_f32 v[18:19], v[18:19], v[18:19]
	v_pk_mul_f32 v[20:21], v[20:21], v[20:21]
	v_pk_mul_f32 v[22:23], v[22:23], v[22:23]
	v_pk_mul_f32 v[24:25], v[24:25], v[24:25]
	v_pk_mul_f32 v[26:27], v[26:27], v[26:27]
	v_pk_mul_f32 v[28:29], v[28:29], v[28:29]
	v_pk_mul_f32 v[30:31], v[30:31], v[30:31]
	v_pk_mul_f32 v[32:33], v[32:33], v[32:33]
	v_lshl_add_u64 v[204:205], v[204:205], 0, v[134:135]
	v_cvt_pk_bf16_f32 v30, v30, v31
	v_cvt_pk_bf16_f32 v31, v32, v33
	v_cvt_pk_bf16_f32 v32, v26, v27
	v_cvt_pk_bf16_f32 v33, v28, v29
	v_lshl_add_u64 v[206:207], v[204:205], 0, s[14:15]
	global_store_dwordx4 v[204:205], v[30:33], off
	v_cvt_pk_bf16_f32 v22, v22, v23
	v_cvt_pk_bf16_f32 v23, v24, v25
	v_cvt_pk_bf16_f32 v24, v18, v19
	v_cvt_pk_bf16_f32 v25, v20, v21
	global_store_dwordx4 v[206:207], v[22:25], off
	v_pk_mul_f32 v[2:3], v[2:3], v[250:251] op_sel:[0,1]
	v_pk_mul_f32 v[4:5], v[4:5], v[250:251] op_sel:[0,1]
	v_pk_mul_f32 v[6:7], v[6:7], v[250:251] op_sel:[0,1]
	v_pk_mul_f32 v[8:9], v[8:9], v[250:251] op_sel:[0,1]
	v_pk_mul_f32 v[10:11], v[10:11], v[250:251] op_sel:[0,1]
	v_pk_mul_f32 v[12:13], v[12:13], v[250:251] op_sel:[0,1]
	v_pk_mul_f32 v[14:15], v[14:15], v[250:251] op_sel:[0,1]
	v_pk_mul_f32 v[16:17], v[16:17], v[250:251] op_sel:[0,1]
	v_lshl_add_u64 v[204:205], s[10:11], 0, v[158:159]
	v_max_f32_e32 v2, 0, v2
	v_max_f32_e32 v3, 0, v3
	v_max_f32_e32 v4, 0, v4
	v_max_f32_e32 v5, 0, v5
	v_max_f32_e32 v6, 0, v6
	v_max_f32_e32 v7, 0, v7
	v_max_f32_e32 v8, 0, v8
	v_max_f32_e32 v9, 0, v9
	v_max_f32_e32 v10, 0, v10
	v_max_f32_e32 v11, 0, v11
	v_max_f32_e32 v12, 0, v12
	v_max_f32_e32 v13, 0, v13
	v_max_f32_e32 v14, 0, v14
	v_max_f32_e32 v15, 0, v15
	v_max_f32_e32 v16, 0, v16
	v_max_f32_e32 v17, 0, v17
	v_lshl_add_u64 v[204:205], v[204:205], 0, s[62:63]
	v_pk_mul_f32 v[2:3], v[2:3], v[2:3]
	v_pk_mul_f32 v[4:5], v[4:5], v[4:5]
	v_pk_mul_f32 v[6:7], v[6:7], v[6:7]
	v_pk_mul_f32 v[8:9], v[8:9], v[8:9]
	v_pk_mul_f32 v[10:11], v[10:11], v[10:11]
	v_pk_mul_f32 v[12:13], v[12:13], v[12:13]
	v_pk_mul_f32 v[14:15], v[14:15], v[14:15]
	v_pk_mul_f32 v[16:17], v[16:17], v[16:17]
	v_lshl_add_u64 v[204:205], v[204:205], 0, v[134:135]
	v_cvt_pk_bf16_f32 v14, v14, v15
	v_cvt_pk_bf16_f32 v15, v16, v17
	v_cvt_pk_bf16_f32 v16, v10, v11
	v_cvt_pk_bf16_f32 v17, v12, v13
	v_lshl_add_u64 v[206:207], v[204:205], 0, s[14:15]
	global_store_dwordx4 v[204:205], v[14:17], off
	v_cvt_pk_bf16_f32 v6, v6, v7
	v_cvt_pk_bf16_f32 v7, v8, v9
	v_cvt_pk_bf16_f32 v8, v2, v3
	v_cvt_pk_bf16_f32 v9, v4, v5
	global_store_dwordx4 v[206:207], v[6:9], off
	s_mov_b64 s[6:7], -1
	s_andn2_b64 vcc, exec, s[36:37]
	s_cbranch_vccnz .LBB0_704
	s_andn2_b64 vcc, exec, s[96:97]
	s_cbranch_vccnz .LBB0_703
	s_barrier
	s_branch .LBB0_703

;     __device__ __forceinline__ void operator()(const f32x4 (&acc)[2][2][4][2], const Unit& u, int wr, int wc, int fr, int fq) const {
; #pragma unroll
;         for (int ai = 0; ai < 2; ++ai)
; #pragma unroll
;             for (int m = 0; m < 4; ++m) {
;                 const size_t row = (size_t)u.pm * 256 + 128 * wr + 64 * ai + 16 * m + fr;
;                 const size_t off = row * DM + 256 * u.pn + 32 * wc + 8 * fq;
; #pragma unroll
;                 for (int bj = 0; bj < 2; ++bj) {
;                     const u32x4 xr = *(const u32x4*)(XB + off + 128 * bj);
;                     f32x4 v0, v1;
;                     v0[0] = __builtin_bit_cast(float, xr[0] << 16); v0[1] = __builtin_bit_cast(float, xr[0] & 0xffff0000u); v0[2] = __builtin_bit_cast(float, xr[1] << 16); v0[3] = __builtin_bit_cast(float, xr[1] & 0xffff0000u);
;                     v1[0] = __builtin_bit_cast(float, xr[2] << 16); v1[1] = __builtin_bit_cast(float, xr[2] & 0xffff0000u); v1[2] = __builtin_bit_cast(float, xr[3] << 16); v1[3] = __builtin_bit_cast(float, xr[3] & 0xffff0000u);
;                     *(f32x4*)(out + off + 128 * bj) = v0 + acc[ai][bj][m][0]; *(f32x4*)(out + off + 128 * bj + 4) = v1 + acc[ai][bj][m][1];
;                 }
;             }
.LBB0_783:
	s_ashr_i32 s97, s96, 31
	s_lshl_b32 s9, s29, 8
	s_ashr_i32 s11, s9, 31
	s_lshl_b64 s[12:13], s[96:97], 18
	v_mov_b32_e32 v147, s11
	v_or_b32_e32 v146, s9, v134
	v_lshl_add_u64 v[154:155], s[12:13], 0, v[144:145]
	v_lshl_add_u64 v[146:147], v[154:155], 0, v[146:147]
	v_lshl_add_u64 v[158:159], v[146:147], 1, s[42:43]
	global_load_dwordx4 v[154:157], v[158:159], off
	s_mov_b64 s[12:13], 0x4000
	s_andn2_b64 vcc, exec, s[36:37]
	s_waitcnt vmcnt(0)
	v_lshlrev_b32_e32 v160, 16, v154
	v_and_b32_e32 v161, 0xffff0000, v154
	v_lshlrev_b32_e32 v154, 16, v155
	v_and_b32_e32 v155, 0xffff0000, v155
	v_lshlrev_b32_e32 v162, 16, v156
	v_and_b32_e32 v163, 0xffff0000, v156
	v_lshlrev_b32_e32 v156, 16, v157
	v_and_b32_e32 v157, 0xffff0000, v157
	v_pk_add_f32 v[128:129], v[128:129], v[154:155]
	v_pk_add_f32 v[126:127], v[126:127], v[160:161]
	v_lshl_add_u64 v[154:155], v[146:147], 2, s[54:55]
	v_pk_add_f32 v[124:125], v[124:125], v[156:157]
	v_pk_add_f32 v[122:123], v[122:123], v[162:163]
	global_store_dwordx4 v[154:155], v[126:129], off
	global_store_dwordx4 v[154:155], v[122:125], off offset:16
	global_load_dwordx4 v[122:125], v[158:159], off offset:256
	s_waitcnt vmcnt(0)
	v_lshlrev_b32_e32 v126, 16, v122
	v_and_b32_e32 v127, 0xffff0000, v122
	v_lshlrev_b32_e32 v122, 16, v123
	v_and_b32_e32 v123, 0xffff0000, v123
	v_lshlrev_b32_e32 v128, 16, v124
	v_and_b32_e32 v129, 0xffff0000, v124
	v_lshlrev_b32_e32 v124, 16, v125
	v_and_b32_e32 v125, 0xffff0000, v125
	v_pk_add_f32 v[120:121], v[120:121], v[122:123]
	v_pk_add_f32 v[118:119], v[118:119], v[126:127]
	global_store_dwordx4 v[154:155], v[118:121], off offset:512
	v_pk_add_f32 v[116:117], v[116:117], v[124:125]
	v_pk_add_f32 v[114:115], v[114:115], v[128:129]
	v_lshl_add_u64 v[118:119], v[146:147], 0, s[12:13]
	global_store_dwordx4 v[154:155], v[114:117], off offset:528
	v_lshl_add_u64 v[120:121], v[118:119], 1, s[42:43]
	global_load_dwordx4 v[114:117], v[120:121], off
	s_mov_b64 s[12:13], 0x8000
	s_waitcnt vmcnt(0)
	v_lshlrev_b32_e32 v122, 16, v114
	v_and_b32_e32 v123, 0xffff0000, v114
	v_lshlrev_b32_e32 v114, 16, v115
	v_and_b32_e32 v115, 0xffff0000, v115
	v_lshlrev_b32_e32 v124, 16, v116
	v_and_b32_e32 v125, 0xffff0000, v116
	v_lshlrev_b32_e32 v116, 16, v117
	v_and_b32_e32 v117, 0xffff0000, v117
	v_pk_add_f32 v[112:113], v[112:113], v[114:115]
	v_pk_add_f32 v[110:111], v[110:111], v[122:123]
	v_lshl_add_u64 v[114:115], v[118:119], 2, s[54:55]
	v_pk_add_f32 v[108:109], v[108:109], v[116:117]
	v_pk_add_f32 v[106:107], v[106:107], v[124:125]
	global_store_dwordx4 v[114:115], v[110:113], off
	global_store_dwordx4 v[114:115], v[106:109], off offset:16
	global_load_dwordx4 v[106:109], v[120:121], off offset:256
	s_waitcnt vmcnt(0)
	v_lshlrev_b32_e32 v110, 16, v106
	v_and_b32_e32 v111, 0xffff0000, v106
	v_lshlrev_b32_e32 v106, 16, v107
	v_and_b32_e32 v107, 0xffff0000, v107
	v_lshlrev_b32_e32 v112, 16, v108
	v_and_b32_e32 v113, 0xffff0000, v108
	v_lshlrev_b32_e32 v108, 16, v109
	v_and_b32_e32 v109, 0xffff0000, v109
	v_pk_add_f32 v[104:105], v[104:105], v[106:107]
	v_pk_add_f32 v[102:103], v[102:103], v[110:111]
	global_store_dwordx4 v[114:115], v[102:105], off offset:512
	v_pk_add_f32 v[100:101], v[100:101], v[108:109]
	v_pk_add_f32 v[98:99], v[98:99], v[112:113]
	v_lshl_add_u64 v[102:103], v[146:147], 0, s[12:13]
	global_store_dwordx4 v[114:115], v[98:101], off offset:528
	v_lshl_add_u64 v[104:105], v[102:103], 1, s[42:43]
	global_load_dwordx4 v[98:101], v[104:105], off
	s_mov_b64 s[12:13], 0xc000
	s_waitcnt vmcnt(0)
	v_lshlrev_b32_e32 v106, 16, v98
	v_and_b32_e32 v107, 0xffff0000, v98
	v_lshlrev_b32_e32 v98, 16, v99
	v_and_b32_e32 v99, 0xffff0000, v99
	v_lshlrev_b32_e32 v108, 16, v100
	v_and_b32_e32 v109, 0xffff0000, v100
	v_lshlrev_b32_e32 v100, 16, v101
	v_and_b32_e32 v101, 0xffff0000, v101
	v_pk_add_f32 v[96:97], v[96:97], v[98:99]
	v_pk_add_f32 v[94:95], v[94:95], v[106:107]
	v_lshl_add_u64 v[98:99], v[102:103], 2, s[54:55]
	v_pk_add_f32 v[92:93], v[92:93], v[100:101]
	v_pk_add_f32 v[90:91], v[90:91], v[108:109]
	global_store_dwordx4 v[98:99], v[94:97], off
	global_store_dwordx4 v[98:99], v[90:93], off offset:16
	global_load_dwordx4 v[90:93], v[104:105], off offset:256
	s_waitcnt vmcnt(0)
	v_lshlrev_b32_e32 v94, 16, v90
	v_and_b32_e32 v95, 0xffff0000, v90
	v_lshlrev_b32_e32 v90, 16, v91
	v_and_b32_e32 v91, 0xffff0000, v91
	v_lshlrev_b32_e32 v96, 16, v92
	v_and_b32_e32 v97, 0xffff0000, v92
	v_lshlrev_b32_e32 v92, 16, v93
	v_and_b32_e32 v93, 0xffff0000, v93
	v_pk_add_f32 v[88:89], v[88:89], v[90:91]
	v_pk_add_f32 v[86:87], v[86:87], v[94:95]
	global_store_dwordx4 v[98:99], v[86:89], off offset:512
	v_pk_add_f32 v[84:85], v[84:85], v[92:93]
	v_pk_add_f32 v[82:83], v[82:83], v[96:97]
	v_lshl_add_u64 v[86:87], v[146:147], 0, s[12:13]
	global_store_dwordx4 v[98:99], v[82:85], off offset:528
	v_lshl_add_u64 v[88:89], v[86:87], 1, s[42:43]
	global_load_dwordx4 v[82:85], v[88:89], off
	s_mov_b64 s[12:13], 0x10000
	s_waitcnt vmcnt(0)
	v_lshlrev_b32_e32 v90, 16, v82
	v_and_b32_e32 v91, 0xffff0000, v82
	v_lshlrev_b32_e32 v82, 16, v83
	v_and_b32_e32 v83, 0xffff0000, v83
	v_lshlrev_b32_e32 v92, 16, v84
	v_and_b32_e32 v93, 0xffff0000, v84
	v_lshlrev_b32_e32 v84, 16, v85
	v_and_b32_e32 v85, 0xffff0000, v85
	v_pk_add_f32 v[80:81], v[80:81], v[82:83]
	v_pk_add_f32 v[78:79], v[78:79], v[90:91]
	v_lshl_add_u64 v[82:83], v[86:87], 2, s[54:55]
	v_pk_add_f32 v[76:77], v[76:77], v[84:85]
	v_pk_add_f32 v[74:75], v[74:75], v[92:93]
	global_store_dwordx4 v[82:83], v[78:81], off
	global_store_dwordx4 v[82:83], v[74:77], off offset:16
	global_load_dwordx4 v[74:77], v[88:89], off offset:256
	s_waitcnt vmcnt(0)
;     __device__ __forceinline__ void operator()(const f32x4 (&acc)[2][2][4][2], const Unit& u, int wr, int wc, int fr, int fq) const {
; #pragma unroll
;         for (int ai = 0; ai < 2; ++ai)
; #pragma unroll
;             for (int m = 0; m < 4; ++m) {
;                 const size_t row = (size_t)u.pm * 256 + 128 * wr + 64 * ai + 16 * m + fr;
;                 const size_t off = row * DM + 256 * u.pn + 32 * wc + 8 * fq;
; #pragma unroll
;                 for (int bj = 0; bj < 2; ++bj) {
;                     const u32x4 xr = *(const u32x4*)(XB + off + 128 * bj);
;                     f32x4 v0, v1;
;                     v0[0] = __builtin_bit_cast(float, xr[0] << 16); v0[1] = __builtin_bit_cast(float, xr[0] & 0xffff0000u); v0[2] = __builtin_bit_cast(float, xr[1] << 16); v0[3] = __builtin_bit_cast(float, xr[1] & 0xffff0000u);
;                     v1[0] = __builtin_bit_cast(float, xr[2] << 16); v1[1] = __builtin_bit_cast(float, xr[2] & 0xffff0000u); v1[2] = __builtin_bit_cast(float, xr[3] << 16); v1[3] = __builtin_bit_cast(float, xr[3] & 0xffff0000u);
;                     *(f32x4*)(out + off + 128 * bj) = v0 + acc[ai][bj][m][0]; *(f32x4*)(out + off + 128 * bj + 4) = v1 + acc[ai][bj][m][1];
;                 }
;             }
	v_lshlrev_b32_e32 v78, 16, v74
	v_and_b32_e32 v79, 0xffff0000, v74
	v_lshlrev_b32_e32 v74, 16, v75
	v_and_b32_e32 v75, 0xffff0000, v75
	v_lshlrev_b32_e32 v80, 16, v76
	v_and_b32_e32 v81, 0xffff0000, v76
	v_lshlrev_b32_e32 v76, 16, v77
	v_and_b32_e32 v77, 0xffff0000, v77
	v_pk_add_f32 v[72:73], v[72:73], v[74:75]
	v_pk_add_f32 v[70:71], v[70:71], v[78:79]
	global_store_dwordx4 v[82:83], v[70:73], off offset:512
	v_pk_add_f32 v[68:69], v[68:69], v[76:77]
	v_pk_add_f32 v[66:67], v[66:67], v[80:81]
	v_lshl_add_u64 v[70:71], v[146:147], 0, s[12:13]
	global_store_dwordx4 v[82:83], v[66:69], off offset:528
	v_lshl_add_u64 v[72:73], v[70:71], 1, s[42:43]
	global_load_dwordx4 v[66:69], v[72:73], off
	s_mov_b64 s[12:13], 0x14000
	s_waitcnt vmcnt(0)
	v_lshlrev_b32_e32 v74, 16, v66
	v_and_b32_e32 v75, 0xffff0000, v66
	v_lshlrev_b32_e32 v66, 16, v67
	v_and_b32_e32 v67, 0xffff0000, v67
	v_lshlrev_b32_e32 v76, 16, v68
	v_and_b32_e32 v77, 0xffff0000, v68
	v_lshlrev_b32_e32 v68, 16, v69
	v_and_b32_e32 v69, 0xffff0000, v69
	v_pk_add_f32 v[64:65], v[64:65], v[66:67]
	v_pk_add_f32 v[62:63], v[62:63], v[74:75]
	v_lshl_add_u64 v[66:67], v[70:71], 2, s[54:55]
	v_pk_add_f32 v[60:61], v[60:61], v[68:69]
	v_pk_add_f32 v[58:59], v[58:59], v[76:77]
	global_store_dwordx4 v[66:67], v[62:65], off
	global_store_dwordx4 v[66:67], v[58:61], off offset:16
	global_load_dwordx4 v[58:61], v[72:73], off offset:256
	s_waitcnt vmcnt(0)
	v_lshlrev_b32_e32 v62, 16, v58
	v_and_b32_e32 v63, 0xffff0000, v58
	v_lshlrev_b32_e32 v58, 16, v59
	v_and_b32_e32 v59, 0xffff0000, v59
	v_lshlrev_b32_e32 v64, 16, v60
	v_and_b32_e32 v65, 0xffff0000, v60
	v_lshlrev_b32_e32 v60, 16, v61
	v_and_b32_e32 v61, 0xffff0000, v61
	v_pk_add_f32 v[56:57], v[56:57], v[58:59]
	v_pk_add_f32 v[54:55], v[54:55], v[62:63]
	global_store_dwordx4 v[66:67], v[54:57], off offset:512
	v_pk_add_f32 v[52:53], v[52:53], v[60:61]
	v_pk_add_f32 v[50:51], v[50:51], v[64:65]
	v_lshl_add_u64 v[54:55], v[146:147], 0, s[12:13]
	global_store_dwordx4 v[66:67], v[50:53], off offset:528
	v_lshl_add_u64 v[56:57], v[54:55], 1, s[42:43]
	global_load_dwordx4 v[50:53], v[56:57], off
	s_mov_b64 s[12:13], 0x18000
	s_waitcnt vmcnt(0)
	v_lshlrev_b32_e32 v58, 16, v50
	v_and_b32_e32 v59, 0xffff0000, v50
	v_lshlrev_b32_e32 v50, 16, v51
	v_and_b32_e32 v51, 0xffff0000, v51
	v_lshlrev_b32_e32 v60, 16, v52
	v_and_b32_e32 v61, 0xffff0000, v52
	v_lshlrev_b32_e32 v52, 16, v53
	v_and_b32_e32 v53, 0xffff0000, v53
	v_pk_add_f32 v[48:49], v[48:49], v[50:51]
	v_pk_add_f32 v[46:47], v[46:47], v[58:59]
	v_lshl_add_u64 v[50:51], v[54:55], 2, s[54:55]
	v_pk_add_f32 v[44:45], v[44:45], v[52:53]
	v_pk_add_f32 v[42:43], v[42:43], v[60:61]
	global_store_dwordx4 v[50:51], v[46:49], off
	global_store_dwordx4 v[50:51], v[42:45], off offset:16
	global_load_dwordx4 v[42:45], v[56:57], off offset:256
	s_waitcnt vmcnt(0)
	v_lshlrev_b32_e32 v46, 16, v42
	v_and_b32_e32 v47, 0xffff0000, v42
	v_lshlrev_b32_e32 v42, 16, v43
	v_and_b32_e32 v43, 0xffff0000, v43
	v_lshlrev_b32_e32 v48, 16, v44
	v_and_b32_e32 v49, 0xffff0000, v44
	v_lshlrev_b32_e32 v44, 16, v45
	v_and_b32_e32 v45, 0xffff0000, v45
	v_pk_add_f32 v[40:41], v[40:41], v[42:43]
	v_pk_add_f32 v[38:39], v[38:39], v[46:47]
	global_store_dwordx4 v[50:51], v[38:41], off offset:512
	v_pk_add_f32 v[36:37], v[36:37], v[44:45]
	v_pk_add_f32 v[34:35], v[34:35], v[48:49]
	v_lshl_add_u64 v[38:39], v[146:147], 0, s[12:13]
	global_store_dwordx4 v[50:51], v[34:37], off offset:528
	v_lshl_add_u64 v[40:41], v[38:39], 1, s[42:43]
	global_load_dwordx4 v[34:37], v[40:41], off
	s_mov_b64 s[12:13], 0x1c000
	s_waitcnt vmcnt(0)
	v_lshlrev_b32_e32 v42, 16, v34
	v_and_b32_e32 v43, 0xffff0000, v34
	v_lshlrev_b32_e32 v34, 16, v35
	v_and_b32_e32 v35, 0xffff0000, v35
	v_lshlrev_b32_e32 v44, 16, v36
	v_and_b32_e32 v45, 0xffff0000, v36
	v_lshlrev_b32_e32 v36, 16, v37
	v_and_b32_e32 v37, 0xffff0000, v37
	v_pk_add_f32 v[32:33], v[32:33], v[34:35]
	v_pk_add_f32 v[30:31], v[30:31], v[42:43]
	v_lshl_add_u64 v[34:35], v[38:39], 2, s[54:55]
	v_pk_add_f32 v[28:29], v[28:29], v[36:37]
	v_pk_add_f32 v[26:27], v[26:27], v[44:45]
	global_store_dwordx4 v[34:35], v[30:33], off
	global_store_dwordx4 v[34:35], v[26:29], off offset:16
	global_load_dwordx4 v[26:29], v[40:41], off offset:256
	s_waitcnt vmcnt(0)
	v_lshlrev_b32_e32 v30, 16, v26
	v_and_b32_e32 v31, 0xffff0000, v26
	v_lshlrev_b32_e32 v26, 16, v27
	v_and_b32_e32 v27, 0xffff0000, v27
	v_lshlrev_b32_e32 v32, 16, v28
	v_and_b32_e32 v33, 0xffff0000, v28
	v_lshlrev_b32_e32 v28, 16, v29
	v_and_b32_e32 v29, 0xffff0000, v29
	v_pk_add_f32 v[24:25], v[24:25], v[26:27]
	v_pk_add_f32 v[22:23], v[22:23], v[30:31]
	global_store_dwordx4 v[34:35], v[22:25], off offset:512
	v_pk_add_f32 v[20:21], v[20:21], v[28:29]
	v_pk_add_f32 v[18:19], v[18:19], v[32:33]
	v_lshl_add_u64 v[22:23], v[146:147], 0, s[12:13]
	global_store_dwordx4 v[34:35], v[18:21], off offset:528
	v_lshl_add_u64 v[24:25], v[22:23], 1, s[42:43]
	global_load_dwordx4 v[18:21], v[24:25], off
	s_mov_b64 s[12:13], -1
	s_waitcnt vmcnt(0)
	v_lshlrev_b32_e32 v26, 16, v18
	v_and_b32_e32 v27, 0xffff0000, v18
	v_lshlrev_b32_e32 v18, 16, v19
	v_and_b32_e32 v19, 0xffff0000, v19
	v_lshlrev_b32_e32 v28, 16, v20
	v_and_b32_e32 v29, 0xffff0000, v20
	v_lshlrev_b32_e32 v20, 16, v21
	v_and_b32_e32 v21, 0xffff0000, v21
	v_pk_add_f32 v[16:17], v[16:17], v[18:19]
	v_pk_add_f32 v[14:15], v[14:15], v[26:27]
	v_lshl_add_u64 v[18:19], v[22:23], 2, s[54:55]
	v_pk_add_f32 v[12:13], v[12:13], v[20:21]
	v_pk_add_f32 v[10:11], v[10:11], v[28:29]
	global_store_dwordx4 v[18:19], v[14:17], off
	global_store_dwordx4 v[18:19], v[10:13], off offset:16
	global_load_dwordx4 v[10:13], v[24:25], off offset:256
	s_waitcnt vmcnt(0)
	v_lshlrev_b32_e32 v14, 16, v10
	v_and_b32_e32 v15, 0xffff0000, v10
	v_lshlrev_b32_e32 v10, 16, v11
	v_and_b32_e32 v11, 0xffff0000, v11
	v_lshlrev_b32_e32 v16, 16, v12
	v_and_b32_e32 v17, 0xffff0000, v12
	v_lshlrev_b32_e32 v12, 16, v13
	v_and_b32_e32 v13, 0xffff0000, v13
	v_pk_add_f32 v[8:9], v[8:9], v[10:11]
	v_pk_add_f32 v[6:7], v[6:7], v[14:15]
	v_pk_add_f32 v[4:5], v[4:5], v[12:13]
	v_pk_add_f32 v[2:3], v[2:3], v[16:17]
	global_store_dwordx4 v[18:19], v[6:9], off offset:512
	global_store_dwordx4 v[18:19], v[2:5], off offset:528
	s_cbranch_vccnz .LBB0_772
	s_andn2_b64 vcc, exec, s[4:5]
	s_cbranch_vccnz .LBB0_771
	s_barrier
	s_branch .LBB0_771

; #define LAS __attribute__((address_space(3)))
; __global__ void __launch_bounds__(512, 2) mk_fwd(Args args) {
;     extern __shared__ __attribute__((aligned(16))) unsigned char lds_raw[];
;     LAS unsigned char* lds = (LAS unsigned char*)lds_raw;
;     const int tid = threadIdx.x, lane = tid & 63, wave = __builtin_amdgcn_readfirstlane(tid >> 6);
	.amdhsa_kernel _Z6mk_fwd4Args
		.amdhsa_group_segment_fixed_size 0
		.amdhsa_private_segment_fixed_size 0
		.amdhsa_kernarg_size 392
		.amdhsa_user_sgpr_count 2
		.amdhsa_user_sgpr_dispatch_ptr 0
		.amdhsa_user_sgpr_queue_ptr 0
		.amdhsa_user_sgpr_kernarg_segment_ptr 1
		.amdhsa_user_sgpr_dispatch_id 0
		.amdhsa_user_sgpr_kernarg_preload_length 0
		.amdhsa_user_sgpr_kernarg_preload_offset 0
		.amdhsa_user_sgpr_private_segment_size 0
		.amdhsa_uses_dynamic_stack 0
		.amdhsa_enable_private_segment 0
		.amdhsa_system_sgpr_workgroup_id_x 1
		.amdhsa_system_sgpr_workgroup_id_y 0
		.amdhsa_system_sgpr_workgroup_id_z 0
		.amdhsa_system_sgpr_workgroup_info 0
		.amdhsa_system_vgpr_workitem_id 0
		.amdhsa_next_free_vgpr 252
		.amdhsa_next_free_sgpr 102
		.amdhsa_accum_offset 252
		.amdhsa_reserve_vcc 1
		.amdhsa_float_round_mode_32 0
		.amdhsa_float_round_mode_16_64 0
		.amdhsa_float_denorm_mode_32 3
		.amdhsa_float_denorm_mode_16_64 3
		.amdhsa_dx10_clamp 1
		.amdhsa_ieee_mode 1
		.amdhsa_fp16_overflow 0
		.amdhsa_tg_split 0
		.amdhsa_exception_fp_ieee_invalid_op 0
		.amdhsa_exception_fp_denorm_src 0
		.amdhsa_exception_fp_ieee_div_zero 0
		.amdhsa_exception_fp_ieee_overflow 0
		.amdhsa_exception_fp_ieee_underflow 0
		.amdhsa_exception_fp_ieee_inexact 0
		.amdhsa_exception_int_div_zero 0
	.end_amdhsa_kernel

; #define LAS __attribute__((address_space(3)))
; __global__ void __launch_bounds__(512, 2) mk_fwd(Args args) {
;     extern __shared__ __attribute__((aligned(16))) unsigned char lds_raw[];
;     LAS unsigned char* lds = (LAS unsigned char*)lds_raw;
;     const int tid = threadIdx.x, lane = tid & 63, wave = __builtin_amdgcn_readfirstlane(tid >> 6);
amdhsa.kernels:
  - .agpr_count:     0
    .args:
      - .offset:         0
        .size:           136
        .value_kind:     by_value
      - .offset:         136
        .size:           4
        .value_kind:     hidden_block_count_x
      - .offset:         140
        .size:           4
        .value_kind:     hidden_block_count_y
      - .offset:         144
        .size:           4
        .value_kind:     hidden_block_count_z
      - .offset:         148
        .size:           2
        .value_kind:     hidden_group_size_x
      - .offset:         150
        .size:           2
        .value_kind:     hidden_group_size_y
      - .offset:         152
        .size:           2
        .value_kind:     hidden_group_size_z
      - .offset:         154
        .size:           2
        .value_kind:     hidden_remainder_x
      - .offset:         156
        .size:           2
        .value_kind:     hidden_remainder_y
      - .offset:         158
        .size:           2
        .value_kind:     hidden_remainder_z
      - .offset:         176
        .size:           8
        .value_kind:     hidden_global_offset_x
      - .offset:         184
        .size:           8
        .value_kind:     hidden_global_offset_y
      - .offset:         192
        .size:           8
        .value_kind:     hidden_global_offset_z
      - .offset:         200
        .size:           2
        .value_kind:     hidden_grid_dims
      - .offset:         256
        .size:           4
        .value_kind:     hidden_dynamic_lds_size
    .group_segment_fixed_size: 0
    .kernarg_segment_align: 8
    .kernarg_segment_size: 392
    .language:       OpenCL C
    .language_version:
      - 2
      - 0
    .max_flat_workgroup_size: 512
    .name:           _Z6mk_fwd4Args
    .private_segment_fixed_size: 0
    .sgpr_count:     108
    .sgpr_spill_count: 76
    .symbol:         _Z6mk_fwd4Args.kd
    .uniform_work_group_size: 1
    .uses_dynamic_stack: false
    .vgpr_count:     252
    .vgpr_spill_count: 0
    .wavefront_size: 64
